# GEMM K-loops: all per-segment s_setprio flips removed (no priority changes)
# baseline (speedup 1.0000x reference)
; #define PG8_STAGE(bufoff, gbase, voff) do { _Pragma("unroll") for (int _i = 0; _i < 2; ++_i) \
;         __builtin_amdgcn_global_load_lds((const unsigned*)((const char*)(gbase) + (voff)[_i]), (PG8_LAS unsigned*)(lds + (bufoff) + ldsw + _i * 8192), 16, 0, 0); } while (0)
; #define PG8_LDA(dst, b, h) do { _Pragma("unroll") for (int m = 0; m < 4; ++m) _Pragma("unroll") for (int k = 0; k < 2; ++k) dst[m][k] = *(const PG8_LAS bf16x8*)(lds + PG8_SA(b, h) + aoff + m * 2048 + k * 1024); } while (0)
; #define PG8_LDB(dst, b, h) do { _Pragma("unroll") for (int n = 0; n < 2; ++n) _Pragma("unroll") for (int k = 0; k < 2; ++k) dst[n][k] = *(const PG8_LAS bf16x8*)(lds + PG8_SB(b, h) + boff + n * 2048 + k * 1024); } while (0)
; #define PG8_MMA(ai, bj, At, Bt) do { __builtin_amdgcn_s_setprio(1); _Pragma("unroll") for (int m = 0; m < 4; ++m) _Pragma("unroll") for (int n = 0; n < 2; ++n) _Pragma("unroll") for (int k = 0; k < 2; ++k) \
;         acc[ai][bj][m][n] = __builtin_amdgcn_mfma_f32_16x16x32_bf16(Bt[n][k], At[m][k], acc[ai][bj][m][n], 0, 0, 0); __builtin_amdgcn_s_setprio(0); } while (0)
; #define PG8_WAIT_V(n) asm volatile("s_waitcnt vmcnt(" #n ")" ::: "memory")
; #define PG8_BAR __builtin_amdgcn_s_barrier()
; template <class Epi, class Sched, bool ALIGN_EPI = false, bool SP2 = false>
; __device__ __forceinline__ void gemm_phase(PG8_LAS unsigned char* lds, const Gemm g, const Sched& S, const Epi& E, int wid_in) {
;     ...
;         for (int t = 0; t < nt; t += 2) {
;             const bool last = (t == nt - 2);
;             const char* a1 = cA + (size_t)(t + 1) * kstep;
;             const char* a2 = last ? nA : cA + (size_t)(t + 2) * kstep; const char* b2 = last ? nB : cB + (size_t)(t + 2) * kstep;
;             const char* a3 = a2 + kstep; const char* b3 = b2 + kstep;
;             if (last && has_next) S.a_ready(nxt);
;             if constexpr (SP2) {
;             PG8_LDB(B0, 0, 0); PG8_LDB(B1, 0, 1); PG8_SCHED; PG8_LDA(At, 0, 0); PG8_STAGE(PG8_SA(1, 1), a1 + hstep, voffA);
;             PG8_WAIT_V(8); PG8_WAIT_L(0); PG8_BAR; PG8_MMA(0, 0, At, B0); PG8_MMA(0, 1, At, B1); PG8_BAR; PG8_SCHED;
;             PG8_LDA(At, 0, 1); PG8_STAGE(PG8_SB(0, 0), b2, voffB); PG8_STAGE(PG8_SB(0, 1), b2 + hstep, voffB); PG8_STAGE(PG8_SA(0, 0), a2, voffA);
;             PG8_WAIT_V(8); PG8_WAIT_L(0); PG8_BAR; PG8_MMA(1, 0, At, B0); PG8_MMA(1, 1, At, B1); PG8_BAR; PG8_SCHED;
.LBB0_278:
	s_add_u32 s28, s26, 0xfff80080
	s_addc_u32 s29, s27, -1
	s_add_i32 s40, 0, 0x10000
	s_cmp_eq_u32 s63, 28
	s_cselect_b32 s31, s11, s29
	s_cselect_b32 s30, s19, s28
	s_cselect_b32 s29, s17, s65
	s_cselect_b32 s28, s62, s64
	s_add_i32 s41, 0, 0x14000
	v_add_u32_e32 v154, s40, v140
	v_add_u32_e32 v170, s41, v140
	ds_read_b128 v[142:145], v154
	ds_read_b128 v[146:149], v154 offset:1024
	ds_read_b128 v[150:153], v154 offset:2048
	ds_read_b128 v[154:157], v154 offset:3072
	ds_read_b128 v[158:161], v170
	ds_read_b128 v[162:165], v170 offset:1024
	ds_read_b128 v[166:169], v170 offset:2048
	ds_read_b128 v[170:173], v170 offset:3072
	v_lshl_add_u64 v[220:221], s[26:27], 0, v[138:139]
	s_add_i32 m0, s13, 0xc000
	ds_read_b128 v[174:177], v141
	ds_read_b128 v[178:181], v141 offset:1024
	ds_read_b128 v[182:185], v141 offset:2048
	ds_read_b128 v[186:189], v141 offset:3072
	ds_read_b128 v[190:193], v141 offset:4096
	ds_read_b128 v[208:211], v141 offset:5120
	ds_read_b128 v[212:215], v141 offset:6144
	ds_read_b128 v[216:219], v141 offset:7168
	global_load_lds_dwordx4 v[220:221], off
	v_lshl_add_u64 v[220:221], s[26:27], 0, v[136:137]
	s_add_i32 m0, s13, 0xe000
	s_nop 0
	global_load_lds_dwordx4 v[220:221], off
	s_waitcnt vmcnt(8)
	s_waitcnt lgkmcnt(0)
	s_barrier
	s_waitcnt lgkmcnt(0)
	v_mfma_f32_16x16x32_bf16 v[126:129], v[142:145], v[174:177], v[126:129]
	v_mfma_f32_16x16x32_bf16 v[122:125], v[150:153], v[174:177], v[122:125]
	v_mfma_f32_16x16x32_bf16 v[118:121], v[142:145], v[182:185], v[118:121]
	v_mfma_f32_16x16x32_bf16 v[114:117], v[150:153], v[182:185], v[114:117]
	v_mfma_f32_16x16x32_bf16 v[102:105], v[142:145], v[190:193], v[102:105]
	v_mfma_f32_16x16x32_bf16 v[98:101], v[150:153], v[190:193], v[98:101]
	v_mfma_f32_16x16x32_bf16 v[86:89], v[142:145], v[212:215], v[86:89]
	v_mfma_f32_16x16x32_bf16 v[82:85], v[150:153], v[212:215], v[82:85]
	v_mfma_f32_16x16x32_bf16 v[126:129], v[146:149], v[178:181], v[126:129]
	v_mfma_f32_16x16x32_bf16 v[122:125], v[154:157], v[178:181], v[122:125]
	v_mfma_f32_16x16x32_bf16 v[118:121], v[146:149], v[186:189], v[118:121]
	v_mfma_f32_16x16x32_bf16 v[114:117], v[154:157], v[186:189], v[114:117]
	v_mfma_f32_16x16x32_bf16 v[102:105], v[146:149], v[208:211], v[102:105]
	v_mfma_f32_16x16x32_bf16 v[98:101], v[154:157], v[208:211], v[98:101]
	v_mfma_f32_16x16x32_bf16 v[86:89], v[146:149], v[216:219], v[86:89]
	v_mfma_f32_16x16x32_bf16 v[82:85], v[154:157], v[216:219], v[82:85]
	v_mfma_f32_16x16x32_bf16 v[110:113], v[158:161], v[174:177], v[110:113]
	v_mfma_f32_16x16x32_bf16 v[106:109], v[166:169], v[174:177], v[106:109]
	v_mfma_f32_16x16x32_bf16 v[94:97], v[158:161], v[182:185], v[94:97]
	v_mfma_f32_16x16x32_bf16 v[90:93], v[166:169], v[182:185], v[90:93]
	v_mfma_f32_16x16x32_bf16 v[78:81], v[158:161], v[190:193], v[78:81]
	v_mfma_f32_16x16x32_bf16 v[74:77], v[166:169], v[190:193], v[74:77]
	v_mfma_f32_16x16x32_bf16 v[70:73], v[158:161], v[212:215], v[70:73]
	v_mfma_f32_16x16x32_bf16 v[66:69], v[166:169], v[212:215], v[66:69]
	v_mfma_f32_16x16x32_bf16 v[110:113], v[162:165], v[178:181], v[110:113]
	v_mfma_f32_16x16x32_bf16 v[106:109], v[170:173], v[178:181], v[106:109]
	v_mfma_f32_16x16x32_bf16 v[94:97], v[162:165], v[186:189], v[94:97]
	v_mfma_f32_16x16x32_bf16 v[90:93], v[170:173], v[186:189], v[90:93]
	v_mfma_f32_16x16x32_bf16 v[78:81], v[162:165], v[208:211], v[78:81]
	v_mfma_f32_16x16x32_bf16 v[74:77], v[170:173], v[208:211], v[74:77]
	v_mfma_f32_16x16x32_bf16 v[70:73], v[162:165], v[216:219], v[70:73]
	v_mfma_f32_16x16x32_bf16 v[66:69], v[170:173], v[216:219], v[66:69]
	s_barrier
	s_add_i32 s40, s40, s59
	v_lshl_add_u64 v[220:221], s[28:29], 0, v[0:1]
	s_mov_b32 m0, s40
	ds_read_b128 v[174:177], v141 offset:16384
	ds_read_b128 v[178:181], v141 offset:17408
	ds_read_b128 v[182:185], v141 offset:18432
	ds_read_b128 v[186:189], v141 offset:19456
	ds_read_b128 v[190:193], v141 offset:20480
	ds_read_b128 v[208:211], v141 offset:21504
	ds_read_b128 v[212:215], v141 offset:22528
	ds_read_b128 v[216:219], v141 offset:23552
	global_load_lds_dwordx4 v[220:221], off
	s_add_i32 m0, s40, 0x2000
	s_add_u32 s72, s28, 0x80000
	v_lshl_add_u64 v[222:223], s[28:29], 0, v[134:135]
	s_addc_u32 s73, s29, 0
	s_add_i32 s40, s41, s59
	global_load_lds_dwordx4 v[222:223], off
	v_lshl_add_u64 v[224:225], s[72:73], 0, v[0:1]
	s_mov_b32 m0, s40
	v_lshl_add_u64 v[226:227], s[30:31], 0, v[132:133]
	global_load_lds_dwordx4 v[224:225], off
	v_lshl_add_u64 v[224:225], s[72:73], 0, v[134:135]
	s_add_i32 m0, s40, 0x2000
	s_nop 0
	global_load_lds_dwordx4 v[224:225], off
	v_lshl_add_u64 v[224:225], s[30:31], 0, v[130:131]
	s_mov_b32 m0, s13
	s_nop 0
	global_load_lds_dwordx4 v[224:225], off
	s_mov_b32 m0, s36
	s_nop 0
	global_load_lds_dwordx4 v[226:227], off
	s_waitcnt vmcnt(8)
	s_waitcnt lgkmcnt(0)
	s_barrier
; #define PG8_STAGE(bufoff, gbase, voff) do { _Pragma("unroll") for (int _i = 0; _i < 2; ++_i) \
;         __builtin_amdgcn_global_load_lds((const unsigned*)((const char*)(gbase) + (voff)[_i]), (PG8_LAS unsigned*)(lds + (bufoff) + ldsw + _i * 8192), 16, 0, 0); } while (0)
; #define PG8_LDA(dst, b, h) do { _Pragma("unroll") for (int m = 0; m < 4; ++m) _Pragma("unroll") for (int k = 0; k < 2; ++k) dst[m][k] = *(const PG8_LAS bf16x8*)(lds + PG8_SA(b, h) + aoff + m * 2048 + k * 1024); } while (0)
; #define PG8_LDB(dst, b, h) do { _Pragma("unroll") for (int n = 0; n < 2; ++n) _Pragma("unroll") for (int k = 0; k < 2; ++k) dst[n][k] = *(const PG8_LAS bf16x8*)(lds + PG8_SB(b, h) + boff + n * 2048 + k * 1024); } while (0)
; #define PG8_MMA(ai, bj, At, Bt) do { __builtin_amdgcn_s_setprio(1); _Pragma("unroll") for (int m = 0; m < 4; ++m) _Pragma("unroll") for (int n = 0; n < 2; ++n) _Pragma("unroll") for (int k = 0; k < 2; ++k) \
;         acc[ai][bj][m][n] = __builtin_amdgcn_mfma_f32_16x16x32_bf16(Bt[n][k], At[m][k], acc[ai][bj][m][n], 0, 0, 0); __builtin_amdgcn_s_setprio(0); } while (0)
; #define PG8_WAIT_V(n) asm volatile("s_waitcnt vmcnt(" #n ")" ::: "memory")
; #define PG8_WAIT_L(n) asm volatile("s_waitcnt lgkmcnt(" #n ")" ::: "memory")
; #define PG8_BAR __builtin_amdgcn_s_barrier()
; #define PG8_SCHED __builtin_amdgcn_sched_barrier(0)
; template <class Epi, class Sched, bool ALIGN_EPI = false, bool SP2 = false>
; __device__ __forceinline__ void gemm_phase(PG8_LAS unsigned char* lds, const Gemm g, const Sched& S, const Epi& E, int wid_in) {
;     ...
;             PG8_WAIT_V(8); PG8_WAIT_L(0); PG8_BAR; PG8_MMA(1, 0, At, B0); PG8_MMA(1, 1, At, B1); PG8_BAR; PG8_SCHED;
;             PG8_LDB(B0, 1, 0); PG8_LDB(B1, 1, 1); PG8_SCHED; PG8_LDA(At, 1, 0); PG8_STAGE(PG8_SA(0, 1), a2 + hstep, voffA);
;             PG8_WAIT_V(8); PG8_WAIT_L(0); PG8_BAR; PG8_MMA(0, 0, At, B0); PG8_MMA(0, 1, At, B1); PG8_BAR; PG8_SCHED;
	s_waitcnt lgkmcnt(0)
	v_mfma_f32_16x16x32_bf16 v[62:65], v[142:145], v[174:177], v[62:65]
	v_mfma_f32_16x16x32_bf16 v[58:61], v[150:153], v[174:177], v[58:61]
	v_mfma_f32_16x16x32_bf16 v[54:57], v[142:145], v[182:185], v[54:57]
	v_mfma_f32_16x16x32_bf16 v[50:53], v[150:153], v[182:185], v[50:53]
	v_mfma_f32_16x16x32_bf16 v[38:41], v[142:145], v[190:193], v[38:41]
	v_mfma_f32_16x16x32_bf16 v[34:37], v[150:153], v[190:193], v[34:37]
	v_mfma_f32_16x16x32_bf16 v[22:25], v[142:145], v[212:215], v[22:25]
	v_mfma_f32_16x16x32_bf16 v[18:21], v[150:153], v[212:215], v[18:21]
	v_mfma_f32_16x16x32_bf16 v[62:65], v[146:149], v[178:181], v[62:65]
	v_mfma_f32_16x16x32_bf16 v[58:61], v[154:157], v[178:181], v[58:61]
	v_mfma_f32_16x16x32_bf16 v[54:57], v[146:149], v[186:189], v[54:57]
	v_mfma_f32_16x16x32_bf16 v[50:53], v[154:157], v[186:189], v[50:53]
	v_mfma_f32_16x16x32_bf16 v[38:41], v[146:149], v[208:211], v[38:41]
	v_mfma_f32_16x16x32_bf16 v[34:37], v[154:157], v[208:211], v[34:37]
	v_mfma_f32_16x16x32_bf16 v[22:25], v[146:149], v[216:219], v[22:25]
	v_mfma_f32_16x16x32_bf16 v[18:21], v[154:157], v[216:219], v[18:21]
	v_mfma_f32_16x16x32_bf16 v[46:49], v[158:161], v[174:177], v[46:49]
	v_mfma_f32_16x16x32_bf16 v[42:45], v[166:169], v[174:177], v[42:45]
	v_mfma_f32_16x16x32_bf16 v[30:33], v[158:161], v[182:185], v[30:33]
	v_mfma_f32_16x16x32_bf16 v[26:29], v[166:169], v[182:185], v[26:29]
	v_mfma_f32_16x16x32_bf16 v[14:17], v[158:161], v[190:193], v[14:17]
	v_mfma_f32_16x16x32_bf16 v[10:13], v[166:169], v[190:193], v[10:13]
	v_mfma_f32_16x16x32_bf16 v[6:9], v[158:161], v[212:215], v[6:9]
	v_mfma_f32_16x16x32_bf16 v[2:5], v[166:169], v[212:215], v[2:5]
	v_mfma_f32_16x16x32_bf16 v[46:49], v[162:165], v[178:181], v[46:49]
	v_mfma_f32_16x16x32_bf16 v[42:45], v[170:173], v[178:181], v[42:45]
	v_mfma_f32_16x16x32_bf16 v[30:33], v[162:165], v[186:189], v[30:33]
	v_mfma_f32_16x16x32_bf16 v[26:29], v[170:173], v[186:189], v[26:29]
	v_mfma_f32_16x16x32_bf16 v[14:17], v[162:165], v[208:211], v[14:17]
	v_mfma_f32_16x16x32_bf16 v[10:13], v[170:173], v[208:211], v[10:13]
	v_mfma_f32_16x16x32_bf16 v[6:9], v[162:165], v[216:219], v[6:9]
	v_mfma_f32_16x16x32_bf16 v[2:5], v[170:173], v[216:219], v[2:5]
	s_barrier
	s_add_i32 s40, 0, 0x18000
	s_add_i32 s41, 0, 0x1c000
	v_add_u32_e32 v154, s40, v140
	v_add_u32_e32 v170, s41, v140
	ds_read_b128 v[142:145], v154
	ds_read_b128 v[146:149], v154 offset:1024
	ds_read_b128 v[150:153], v154 offset:2048
	ds_read_b128 v[154:157], v154 offset:3072
	ds_read_b128 v[158:161], v170
	ds_read_b128 v[162:165], v170 offset:1024
	ds_read_b128 v[166:169], v170 offset:2048
	ds_read_b128 v[170:173], v170 offset:3072
	s_add_u32 s30, s30, 0x80000
	s_addc_u32 s31, s31, 0
	s_mov_b32 m0, s37
	v_lshl_add_u64 v[228:229], s[30:31], 0, v[130:131]
	ds_read_b128 v[174:177], v141 offset:32768
	ds_read_b128 v[178:181], v141 offset:33792
	ds_read_b128 v[182:185], v141 offset:34816
	ds_read_b128 v[186:189], v141 offset:35840
	ds_read_b128 v[190:193], v141 offset:36864
	ds_read_b128 v[208:211], v141 offset:37888
	ds_read_b128 v[212:215], v141 offset:38912
	ds_read_b128 v[216:219], v141 offset:39936
	global_load_lds_dwordx4 v[228:229], off
	v_lshl_add_u64 v[228:229], s[30:31], 0, v[132:133]
	s_mov_b32 m0, s38
	s_nop 0
	global_load_lds_dwordx4 v[228:229], off
	s_waitcnt vmcnt(8)
	s_waitcnt lgkmcnt(0)
	s_barrier
	s_waitcnt lgkmcnt(0)
	v_mfma_f32_16x16x32_bf16 v[126:129], v[142:145], v[174:177], v[126:129]
	v_mfma_f32_16x16x32_bf16 v[122:125], v[150:153], v[174:177], v[122:125]
	v_mfma_f32_16x16x32_bf16 v[118:121], v[142:145], v[182:185], v[118:121]
	v_mfma_f32_16x16x32_bf16 v[114:117], v[150:153], v[182:185], v[114:117]
	v_mfma_f32_16x16x32_bf16 v[102:105], v[142:145], v[190:193], v[102:105]
	v_mfma_f32_16x16x32_bf16 v[98:101], v[150:153], v[190:193], v[98:101]
	v_mfma_f32_16x16x32_bf16 v[86:89], v[142:145], v[212:215], v[86:89]
	v_mfma_f32_16x16x32_bf16 v[82:85], v[150:153], v[212:215], v[82:85]
	v_mfma_f32_16x16x32_bf16 v[126:129], v[146:149], v[178:181], v[126:129]
	v_mfma_f32_16x16x32_bf16 v[122:125], v[154:157], v[178:181], v[122:125]
	v_mfma_f32_16x16x32_bf16 v[118:121], v[146:149], v[186:189], v[118:121]
	v_mfma_f32_16x16x32_bf16 v[114:117], v[154:157], v[186:189], v[114:117]
	v_mfma_f32_16x16x32_bf16 v[102:105], v[146:149], v[208:211], v[102:105]
	v_mfma_f32_16x16x32_bf16 v[98:101], v[154:157], v[208:211], v[98:101]
	v_mfma_f32_16x16x32_bf16 v[86:89], v[146:149], v[216:219], v[86:89]
	v_mfma_f32_16x16x32_bf16 v[82:85], v[154:157], v[216:219], v[82:85]
	v_mfma_f32_16x16x32_bf16 v[110:113], v[158:161], v[174:177], v[110:113]
	v_mfma_f32_16x16x32_bf16 v[106:109], v[166:169], v[174:177], v[106:109]
	v_mfma_f32_16x16x32_bf16 v[94:97], v[158:161], v[182:185], v[94:97]
	v_mfma_f32_16x16x32_bf16 v[90:93], v[166:169], v[182:185], v[90:93]
	v_mfma_f32_16x16x32_bf16 v[78:81], v[158:161], v[190:193], v[78:81]
	v_mfma_f32_16x16x32_bf16 v[74:77], v[166:169], v[190:193], v[74:77]
	v_mfma_f32_16x16x32_bf16 v[70:73], v[158:161], v[212:215], v[70:73]
	v_mfma_f32_16x16x32_bf16 v[66:69], v[166:169], v[212:215], v[66:69]
	v_mfma_f32_16x16x32_bf16 v[110:113], v[162:165], v[178:181], v[110:113]
	v_mfma_f32_16x16x32_bf16 v[106:109], v[170:173], v[178:181], v[106:109]
	v_mfma_f32_16x16x32_bf16 v[94:97], v[162:165], v[186:189], v[94:97]
	v_mfma_f32_16x16x32_bf16 v[90:93], v[170:173], v[186:189], v[90:93]
	v_mfma_f32_16x16x32_bf16 v[78:81], v[162:165], v[208:211], v[78:81]
	v_mfma_f32_16x16x32_bf16 v[74:77], v[170:173], v[208:211], v[74:77]
	v_mfma_f32_16x16x32_bf16 v[70:73], v[162:165], v[216:219], v[70:73]
	v_mfma_f32_16x16x32_bf16 v[66:69], v[170:173], v[216:219], v[66:69]
	s_barrier
; #define PG8_STAGE(bufoff, gbase, voff) do { _Pragma("unroll") for (int _i = 0; _i < 2; ++_i) \
;         __builtin_amdgcn_global_load_lds((const unsigned*)((const char*)(gbase) + (voff)[_i]), (PG8_LAS unsigned*)(lds + (bufoff) + ldsw + _i * 8192), 16, 0, 0); } while (0)
; #define PG8_LDA(dst, b, h) do { _Pragma("unroll") for (int m = 0; m < 4; ++m) _Pragma("unroll") for (int k = 0; k < 2; ++k) dst[m][k] = *(const PG8_LAS bf16x8*)(lds + PG8_SA(b, h) + aoff + m * 2048 + k * 1024); } while (0)
; #define PG8_MMA(ai, bj, At, Bt) do { __builtin_amdgcn_s_setprio(1); _Pragma("unroll") for (int m = 0; m < 4; ++m) _Pragma("unroll") for (int n = 0; n < 2; ++n) _Pragma("unroll") for (int k = 0; k < 2; ++k) \
;         acc[ai][bj][m][n] = __builtin_amdgcn_mfma_f32_16x16x32_bf16(Bt[n][k], At[m][k], acc[ai][bj][m][n], 0, 0, 0); __builtin_amdgcn_s_setprio(0); } while (0)
; #define PG8_WAIT_V(n) asm volatile("s_waitcnt vmcnt(" #n ")" ::: "memory")
; #define PG8_WAIT_L(n) asm volatile("s_waitcnt lgkmcnt(" #n ")" ::: "memory")
; #define PG8_BAR __builtin_amdgcn_s_barrier()
; #define PG8_SCHED __builtin_amdgcn_sched_barrier(0)
; template <class Epi, class Sched, bool ALIGN_EPI = false, bool SP2 = false>
; __device__ __forceinline__ void gemm_phase(PG8_LAS unsigned char* lds, const Gemm g, const Sched& S, const Epi& E, int wid_in) {
;     ...
;         for (int t = 0; t < nt; t += 2) {
;             const bool last = (t == nt - 2);
;             const char* a1 = cA + (size_t)(t + 1) * kstep;
;             const char* a2 = last ? nA : cA + (size_t)(t + 2) * kstep; const char* b2 = last ? nB : cB + (size_t)(t + 2) * kstep;
;             const char* a3 = a2 + kstep; const char* b3 = b2 + kstep;
;             if (last && has_next) S.a_ready(nxt);
;     ...
;             PG8_LDA(At, 1, 1); PG8_STAGE(PG8_SB(1, 0), b3, voffB); PG8_STAGE(PG8_SB(1, 1), b3 + hstep, voffB); PG8_STAGE(PG8_SA(1, 0), a3, voffA);
;             PG8_WAIT_V(8); PG8_WAIT_L(0); PG8_BAR; PG8_MMA(1, 0, At, B0); PG8_MMA(1, 1, At, B1); PG8_BAR; PG8_SCHED;
	s_add_i32 s30, s40, s59
	v_lshl_add_u64 v[220:221], v[220:221], 0, s[94:95]
	s_mov_b32 m0, s30
	ds_read_b128 v[174:177], v141 offset:49152
	ds_read_b128 v[178:181], v141 offset:50176
	ds_read_b128 v[182:185], v141 offset:51200
	ds_read_b128 v[186:189], v141 offset:52224
	ds_read_b128 v[190:193], v141 offset:53248
	ds_read_b128 v[208:211], v141 offset:54272
	ds_read_b128 v[212:215], v141 offset:55296
	ds_read_b128 v[216:219], v141 offset:56320
	global_load_lds_dwordx4 v[220:221], off
	s_add_i32 m0, s30, 0x2000
	s_add_u32 s28, s28, 0x80080
	v_lshl_add_u64 v[220:221], v[222:223], 0, s[94:95]
	s_addc_u32 s29, s29, 0
	s_add_i32 s30, s41, s59
	global_load_lds_dwordx4 v[220:221], off
	v_lshl_add_u64 v[220:221], s[28:29], 0, v[0:1]
	s_mov_b32 m0, s30
	s_nop 0
	global_load_lds_dwordx4 v[220:221], off
	v_lshl_add_u64 v[220:221], s[28:29], 0, v[134:135]
	s_add_i32 m0, s30, 0x2000
	s_nop 0
	global_load_lds_dwordx4 v[220:221], off
	v_lshl_add_u64 v[220:221], v[224:225], 0, s[94:95]
	s_mov_b32 m0, s52
	s_nop 0
	global_load_lds_dwordx4 v[220:221], off
	v_lshl_add_u64 v[220:221], v[226:227], 0, s[94:95]
	s_mov_b32 m0, s53
	s_nop 0
	global_load_lds_dwordx4 v[220:221], off
	s_waitcnt vmcnt(8)
	s_waitcnt lgkmcnt(0)
	s_barrier
	s_waitcnt lgkmcnt(0)
	v_mfma_f32_16x16x32_bf16 v[62:65], v[142:145], v[174:177], v[62:65]
	v_mfma_f32_16x16x32_bf16 v[58:61], v[150:153], v[174:177], v[58:61]
	v_mfma_f32_16x16x32_bf16 v[54:57], v[142:145], v[182:185], v[54:57]
	v_mfma_f32_16x16x32_bf16 v[50:53], v[150:153], v[182:185], v[50:53]
	v_mfma_f32_16x16x32_bf16 v[38:41], v[142:145], v[190:193], v[38:41]
	v_mfma_f32_16x16x32_bf16 v[34:37], v[150:153], v[190:193], v[34:37]
	v_mfma_f32_16x16x32_bf16 v[22:25], v[142:145], v[212:215], v[22:25]
	v_mfma_f32_16x16x32_bf16 v[18:21], v[150:153], v[212:215], v[18:21]
	v_mfma_f32_16x16x32_bf16 v[62:65], v[146:149], v[178:181], v[62:65]
	v_mfma_f32_16x16x32_bf16 v[58:61], v[154:157], v[178:181], v[58:61]
	v_mfma_f32_16x16x32_bf16 v[54:57], v[146:149], v[186:189], v[54:57]
	v_mfma_f32_16x16x32_bf16 v[50:53], v[154:157], v[186:189], v[50:53]
	v_mfma_f32_16x16x32_bf16 v[38:41], v[146:149], v[208:211], v[38:41]
	v_mfma_f32_16x16x32_bf16 v[34:37], v[154:157], v[208:211], v[34:37]
	v_mfma_f32_16x16x32_bf16 v[22:25], v[146:149], v[216:219], v[22:25]
	v_mfma_f32_16x16x32_bf16 v[18:21], v[154:157], v[216:219], v[18:21]
	v_mfma_f32_16x16x32_bf16 v[46:49], v[158:161], v[174:177], v[46:49]
	v_mfma_f32_16x16x32_bf16 v[42:45], v[166:169], v[174:177], v[42:45]
	v_mfma_f32_16x16x32_bf16 v[30:33], v[158:161], v[182:185], v[30:33]
	v_mfma_f32_16x16x32_bf16 v[26:29], v[166:169], v[182:185], v[26:29]
	v_mfma_f32_16x16x32_bf16 v[14:17], v[158:161], v[190:193], v[14:17]
	v_mfma_f32_16x16x32_bf16 v[10:13], v[166:169], v[190:193], v[10:13]
	v_mfma_f32_16x16x32_bf16 v[6:9], v[158:161], v[212:215], v[6:9]
	v_mfma_f32_16x16x32_bf16 v[2:5], v[166:169], v[212:215], v[2:5]
	v_mfma_f32_16x16x32_bf16 v[46:49], v[162:165], v[178:181], v[46:49]
	v_mfma_f32_16x16x32_bf16 v[42:45], v[170:173], v[178:181], v[42:45]
	v_mfma_f32_16x16x32_bf16 v[30:33], v[162:165], v[186:189], v[30:33]
	v_mfma_f32_16x16x32_bf16 v[26:29], v[170:173], v[186:189], v[26:29]
	v_mfma_f32_16x16x32_bf16 v[14:17], v[162:165], v[208:211], v[14:17]
	v_mfma_f32_16x16x32_bf16 v[10:13], v[170:173], v[208:211], v[10:13]
	v_mfma_f32_16x16x32_bf16 v[6:9], v[162:165], v[216:219], v[6:9]
	v_mfma_f32_16x16x32_bf16 v[2:5], v[170:173], v[216:219], v[2:5]
	s_barrier
	s_add_i32 s63, s63, 2
	s_add_u32 s64, s64, 0x100
	s_addc_u32 s65, s65, 0
	s_add_u32 s26, s26, 0x100
	s_addc_u32 s27, s27, 0
	s_cmp_gt_u32 s63, 29
	s_cbranch_scc0 .LBB0_278
	s_and_b64 vcc, exec, s[14:15]
	s_cbranch_vccz .LBB0_281
	s_barrier

; #define PG8_STAGE(bufoff, gbase, voff) do { _Pragma("unroll") for (int _i = 0; _i < 2; ++_i) \
;         __builtin_amdgcn_global_load_lds((const unsigned*)((const char*)(gbase) + (voff)[_i]), (PG8_LAS unsigned*)(lds + (bufoff) + ldsw + _i * 8192), 16, 0, 0); } while (0)
; #define PG8_LDA(dst, b, h) do { _Pragma("unroll") for (int m = 0; m < 4; ++m) _Pragma("unroll") for (int k = 0; k < 2; ++k) dst[m][k] = *(const PG8_LAS bf16x8*)(lds + PG8_SA(b, h) + aoff + m * 2048 + k * 1024); } while (0)
; #define PG8_LDB(dst, b, h) do { _Pragma("unroll") for (int n = 0; n < 2; ++n) _Pragma("unroll") for (int k = 0; k < 2; ++k) dst[n][k] = *(const PG8_LAS bf16x8*)(lds + PG8_SB(b, h) + boff + n * 2048 + k * 1024); } while (0)
; #define PG8_MMA(ai, bj, At, Bt) do { __builtin_amdgcn_s_setprio(1); _Pragma("unroll") for (int m = 0; m < 4; ++m) _Pragma("unroll") for (int n = 0; n < 2; ++n) _Pragma("unroll") for (int k = 0; k < 2; ++k) \
;         acc[ai][bj][m][n] = __builtin_amdgcn_mfma_f32_16x16x32_bf16(Bt[n][k], At[m][k], acc[ai][bj][m][n], 0, 0, 0); __builtin_amdgcn_s_setprio(0); } while (0)
; #define PG8_WAIT_V(n) asm volatile("s_waitcnt vmcnt(" #n ")" ::: "memory")
; #define PG8_BAR __builtin_amdgcn_s_barrier()
; template <class Epi, class Sched, bool ALIGN_EPI = false, bool SP2 = false>
; __device__ __forceinline__ void gemm_phase(PG8_LAS unsigned char* lds, const Gemm g, const Sched& S, const Epi& E, int wid_in) {
;     ...
;         for (int t = 0; t < nt; t += 2) {
;             const bool last = (t == nt - 2);
;             const char* a1 = cA + (size_t)(t + 1) * kstep;
;             const char* a2 = last ? nA : cA + (size_t)(t + 2) * kstep; const char* b2 = last ? nB : cB + (size_t)(t + 2) * kstep;
;             const char* a3 = a2 + kstep; const char* b3 = b2 + kstep;
;             if (last && has_next) S.a_ready(nxt);
;             if constexpr (SP2) {
;             PG8_LDB(B0, 0, 0); PG8_LDB(B1, 0, 1); PG8_SCHED; PG8_LDA(At, 0, 0); PG8_STAGE(PG8_SA(1, 1), a1 + hstep, voffA);
;             PG8_WAIT_V(8); PG8_WAIT_L(0); PG8_BAR; PG8_MMA(0, 0, At, B0); PG8_MMA(0, 1, At, B1); PG8_BAR; PG8_SCHED;
;             PG8_LDA(At, 0, 1); PG8_STAGE(PG8_SB(0, 0), b2, voffB); PG8_STAGE(PG8_SB(0, 1), b2 + hstep, voffB); PG8_STAGE(PG8_SA(0, 0), a2, voffA);
;             PG8_WAIT_V(8); PG8_WAIT_L(0); PG8_BAR; PG8_MMA(1, 0, At, B0); PG8_MMA(1, 1, At, B1); PG8_BAR; PG8_SCHED;
.LBB0_848:
	s_add_i32 s56, s34, 2
	s_add_u32 s35, s30, 0xfffc0080
	s_addc_u32 s36, s31, -1
	s_add_i32 s40, 0, 0x10000
	s_cmp_eq_u32 vcc_lo, s34
	s_cselect_b32 s37, s15, s36
	s_cselect_b32 s36, s19, s35
	s_cselect_b32 s35, s17, s63
	s_cselect_b32 s34, s27, vcc_hi
	s_add_i32 s42, 0, 0x14000
	v_add_u32_e32 v142, s40, v188
	v_add_u32_e32 v158, s42, v188
	ds_read_b128 v[130:133], v142
	ds_read_b128 v[134:137], v142 offset:1024
	ds_read_b128 v[138:141], v142 offset:2048
	ds_read_b128 v[142:145], v142 offset:3072
	ds_read_b128 v[146:149], v158
	ds_read_b128 v[150:153], v158 offset:1024
	ds_read_b128 v[154:157], v158 offset:2048
	ds_read_b128 v[158:161], v158 offset:3072
	v_lshl_add_u64 v[220:221], s[30:31], 0, v[170:171]
	s_add_i32 m0, s29, 0xc000
	ds_read_b128 v[172:175], v189
	ds_read_b128 v[176:179], v189 offset:1024
	ds_read_b128 v[180:183], v189 offset:2048
	ds_read_b128 v[184:187], v189 offset:3072
	ds_read_b128 v[190:193], v189 offset:4096
	ds_read_b128 v[208:211], v189 offset:5120
	ds_read_b128 v[212:215], v189 offset:6144
	ds_read_b128 v[216:219], v189 offset:7168
	global_load_lds_dwordx4 v[220:221], off
	v_lshl_add_u64 v[220:221], s[30:31], 0, v[168:169]
	s_add_i32 m0, s29, 0xe000
	s_nop 0
	global_load_lds_dwordx4 v[220:221], off
	s_waitcnt vmcnt(8)
	s_waitcnt lgkmcnt(0)
	s_barrier
	s_waitcnt lgkmcnt(0)
	v_mfma_f32_16x16x32_bf16 v[126:129], v[130:133], v[172:175], v[126:129]
	v_mfma_f32_16x16x32_bf16 v[122:125], v[138:141], v[172:175], v[122:125]
	v_mfma_f32_16x16x32_bf16 v[118:121], v[130:133], v[180:183], v[118:121]
	v_mfma_f32_16x16x32_bf16 v[114:117], v[138:141], v[180:183], v[114:117]
	v_mfma_f32_16x16x32_bf16 v[102:105], v[130:133], v[190:193], v[102:105]
	v_mfma_f32_16x16x32_bf16 v[98:101], v[138:141], v[190:193], v[98:101]
	v_mfma_f32_16x16x32_bf16 v[86:89], v[130:133], v[212:215], v[86:89]
	v_mfma_f32_16x16x32_bf16 v[82:85], v[138:141], v[212:215], v[82:85]
	v_mfma_f32_16x16x32_bf16 v[126:129], v[134:137], v[176:179], v[126:129]
	v_mfma_f32_16x16x32_bf16 v[122:125], v[142:145], v[176:179], v[122:125]
	v_mfma_f32_16x16x32_bf16 v[118:121], v[134:137], v[184:187], v[118:121]
	v_mfma_f32_16x16x32_bf16 v[114:117], v[142:145], v[184:187], v[114:117]
	v_mfma_f32_16x16x32_bf16 v[102:105], v[134:137], v[208:211], v[102:105]
	v_mfma_f32_16x16x32_bf16 v[98:101], v[142:145], v[208:211], v[98:101]
	v_mfma_f32_16x16x32_bf16 v[86:89], v[134:137], v[216:219], v[86:89]
	v_mfma_f32_16x16x32_bf16 v[82:85], v[142:145], v[216:219], v[82:85]
	v_mfma_f32_16x16x32_bf16 v[110:113], v[146:149], v[172:175], v[110:113]
	v_mfma_f32_16x16x32_bf16 v[106:109], v[154:157], v[172:175], v[106:109]
	v_mfma_f32_16x16x32_bf16 v[94:97], v[146:149], v[180:183], v[94:97]
	v_mfma_f32_16x16x32_bf16 v[90:93], v[154:157], v[180:183], v[90:93]
	v_mfma_f32_16x16x32_bf16 v[78:81], v[146:149], v[190:193], v[78:81]
	v_mfma_f32_16x16x32_bf16 v[74:77], v[154:157], v[190:193], v[74:77]
	v_mfma_f32_16x16x32_bf16 v[70:73], v[146:149], v[212:215], v[70:73]
	v_mfma_f32_16x16x32_bf16 v[66:69], v[154:157], v[212:215], v[66:69]
	v_mfma_f32_16x16x32_bf16 v[110:113], v[150:153], v[176:179], v[110:113]
	v_mfma_f32_16x16x32_bf16 v[106:109], v[158:161], v[176:179], v[106:109]
	v_mfma_f32_16x16x32_bf16 v[94:97], v[150:153], v[184:187], v[94:97]
	v_mfma_f32_16x16x32_bf16 v[90:93], v[158:161], v[184:187], v[90:93]
	v_mfma_f32_16x16x32_bf16 v[78:81], v[150:153], v[208:211], v[78:81]
	v_mfma_f32_16x16x32_bf16 v[74:77], v[158:161], v[208:211], v[74:77]
	v_mfma_f32_16x16x32_bf16 v[70:73], v[150:153], v[216:219], v[70:73]
	v_mfma_f32_16x16x32_bf16 v[66:69], v[158:161], v[216:219], v[66:69]
	s_barrier
	s_add_i32 s40, s40, s59
	v_lshl_add_u64 v[220:221], s[34:35], 0, v[0:1]
	s_mov_b32 m0, s40
	ds_read_b128 v[172:175], v189 offset:16384
	ds_read_b128 v[176:179], v189 offset:17408
	ds_read_b128 v[180:183], v189 offset:18432
	ds_read_b128 v[184:187], v189 offset:19456
	ds_read_b128 v[190:193], v189 offset:20480
	ds_read_b128 v[208:211], v189 offset:21504
	ds_read_b128 v[212:215], v189 offset:22528
	ds_read_b128 v[216:219], v189 offset:23552
	global_load_lds_dwordx4 v[220:221], off
	s_add_i32 m0, s40, 0x2000
	s_add_u32 s40, s34, 0x40000
	v_lshl_add_u64 v[222:223], s[34:35], 0, v[166:167]
	s_addc_u32 s41, s35, 0
	s_add_i32 s42, s42, s59
	global_load_lds_dwordx4 v[222:223], off
	v_lshl_add_u64 v[224:225], s[40:41], 0, v[0:1]
	s_mov_b32 m0, s42
	v_lshl_add_u64 v[226:227], s[36:37], 0, v[164:165]
	global_load_lds_dwordx4 v[224:225], off
	v_lshl_add_u64 v[224:225], s[40:41], 0, v[166:167]
	s_add_i32 m0, s42, 0x2000
	s_nop 0
	global_load_lds_dwordx4 v[224:225], off
	v_lshl_add_u64 v[224:225], s[36:37], 0, v[162:163]
	s_mov_b32 m0, s29
	s_nop 0
	global_load_lds_dwordx4 v[224:225], off
	s_mov_b32 m0, s64
	s_nop 0
	global_load_lds_dwordx4 v[226:227], off
	s_waitcnt vmcnt(8)
	s_waitcnt lgkmcnt(0)
	s_barrier
; #define PG8_STAGE(bufoff, gbase, voff) do { _Pragma("unroll") for (int _i = 0; _i < 2; ++_i) \
;         __builtin_amdgcn_global_load_lds((const unsigned*)((const char*)(gbase) + (voff)[_i]), (PG8_LAS unsigned*)(lds + (bufoff) + ldsw + _i * 8192), 16, 0, 0); } while (0)
; #define PG8_LDA(dst, b, h) do { _Pragma("unroll") for (int m = 0; m < 4; ++m) _Pragma("unroll") for (int k = 0; k < 2; ++k) dst[m][k] = *(const PG8_LAS bf16x8*)(lds + PG8_SA(b, h) + aoff + m * 2048 + k * 1024); } while (0)
; #define PG8_LDB(dst, b, h) do { _Pragma("unroll") for (int n = 0; n < 2; ++n) _Pragma("unroll") for (int k = 0; k < 2; ++k) dst[n][k] = *(const PG8_LAS bf16x8*)(lds + PG8_SB(b, h) + boff + n * 2048 + k * 1024); } while (0)
; #define PG8_MMA(ai, bj, At, Bt) do { __builtin_amdgcn_s_setprio(1); _Pragma("unroll") for (int m = 0; m < 4; ++m) _Pragma("unroll") for (int n = 0; n < 2; ++n) _Pragma("unroll") for (int k = 0; k < 2; ++k) \
;         acc[ai][bj][m][n] = __builtin_amdgcn_mfma_f32_16x16x32_bf16(Bt[n][k], At[m][k], acc[ai][bj][m][n], 0, 0, 0); __builtin_amdgcn_s_setprio(0); } while (0)
; #define PG8_WAIT_V(n) asm volatile("s_waitcnt vmcnt(" #n ")" ::: "memory")
; #define PG8_WAIT_L(n) asm volatile("s_waitcnt lgkmcnt(" #n ")" ::: "memory")
; #define PG8_BAR __builtin_amdgcn_s_barrier()
; #define PG8_SCHED __builtin_amdgcn_sched_barrier(0)
; template <class Epi, class Sched, bool ALIGN_EPI = false, bool SP2 = false>
; __device__ __forceinline__ void gemm_phase(PG8_LAS unsigned char* lds, const Gemm g, const Sched& S, const Epi& E, int wid_in) {
;     ...
;             PG8_WAIT_V(8); PG8_WAIT_L(0); PG8_BAR; PG8_MMA(1, 0, At, B0); PG8_MMA(1, 1, At, B1); PG8_BAR; PG8_SCHED;
;             PG8_LDB(B0, 1, 0); PG8_LDB(B1, 1, 1); PG8_SCHED; PG8_LDA(At, 1, 0); PG8_STAGE(PG8_SA(0, 1), a2 + hstep, voffA);
;             PG8_WAIT_V(8); PG8_WAIT_L(0); PG8_BAR; PG8_MMA(0, 0, At, B0); PG8_MMA(0, 1, At, B1); PG8_BAR; PG8_SCHED;
	s_waitcnt lgkmcnt(0)
	v_mfma_f32_16x16x32_bf16 v[62:65], v[130:133], v[172:175], v[62:65]
	v_mfma_f32_16x16x32_bf16 v[58:61], v[138:141], v[172:175], v[58:61]
	v_mfma_f32_16x16x32_bf16 v[54:57], v[130:133], v[180:183], v[54:57]
	v_mfma_f32_16x16x32_bf16 v[50:53], v[138:141], v[180:183], v[50:53]
	v_mfma_f32_16x16x32_bf16 v[38:41], v[130:133], v[190:193], v[38:41]
	v_mfma_f32_16x16x32_bf16 v[34:37], v[138:141], v[190:193], v[34:37]
	v_mfma_f32_16x16x32_bf16 v[22:25], v[130:133], v[212:215], v[22:25]
	v_mfma_f32_16x16x32_bf16 v[18:21], v[138:141], v[212:215], v[18:21]
	v_mfma_f32_16x16x32_bf16 v[62:65], v[134:137], v[176:179], v[62:65]
	v_mfma_f32_16x16x32_bf16 v[58:61], v[142:145], v[176:179], v[58:61]
	v_mfma_f32_16x16x32_bf16 v[54:57], v[134:137], v[184:187], v[54:57]
	v_mfma_f32_16x16x32_bf16 v[50:53], v[142:145], v[184:187], v[50:53]
	v_mfma_f32_16x16x32_bf16 v[38:41], v[134:137], v[208:211], v[38:41]
	v_mfma_f32_16x16x32_bf16 v[34:37], v[142:145], v[208:211], v[34:37]
	v_mfma_f32_16x16x32_bf16 v[22:25], v[134:137], v[216:219], v[22:25]
	v_mfma_f32_16x16x32_bf16 v[18:21], v[142:145], v[216:219], v[18:21]
	v_mfma_f32_16x16x32_bf16 v[46:49], v[146:149], v[172:175], v[46:49]
	v_mfma_f32_16x16x32_bf16 v[42:45], v[154:157], v[172:175], v[42:45]
	v_mfma_f32_16x16x32_bf16 v[30:33], v[146:149], v[180:183], v[30:33]
	v_mfma_f32_16x16x32_bf16 v[26:29], v[154:157], v[180:183], v[26:29]
	v_mfma_f32_16x16x32_bf16 v[14:17], v[146:149], v[190:193], v[14:17]
	v_mfma_f32_16x16x32_bf16 v[10:13], v[154:157], v[190:193], v[10:13]
	v_mfma_f32_16x16x32_bf16 v[6:9], v[146:149], v[212:215], v[6:9]
	v_mfma_f32_16x16x32_bf16 v[2:5], v[154:157], v[212:215], v[2:5]
	v_mfma_f32_16x16x32_bf16 v[46:49], v[150:153], v[176:179], v[46:49]
	v_mfma_f32_16x16x32_bf16 v[42:45], v[158:161], v[176:179], v[42:45]
	v_mfma_f32_16x16x32_bf16 v[30:33], v[150:153], v[184:187], v[30:33]
	v_mfma_f32_16x16x32_bf16 v[26:29], v[158:161], v[184:187], v[26:29]
	v_mfma_f32_16x16x32_bf16 v[14:17], v[150:153], v[208:211], v[14:17]
	v_mfma_f32_16x16x32_bf16 v[10:13], v[158:161], v[208:211], v[10:13]
	v_mfma_f32_16x16x32_bf16 v[6:9], v[150:153], v[216:219], v[6:9]
	v_mfma_f32_16x16x32_bf16 v[2:5], v[158:161], v[216:219], v[2:5]
	s_barrier
	s_add_i32 s40, 0, 0x18000
	s_add_i32 s41, 0, 0x1c000
	v_add_u32_e32 v142, s40, v188
	v_add_u32_e32 v158, s41, v188
	ds_read_b128 v[130:133], v142
	ds_read_b128 v[134:137], v142 offset:1024
	ds_read_b128 v[138:141], v142 offset:2048
	ds_read_b128 v[142:145], v142 offset:3072
	ds_read_b128 v[146:149], v158
	ds_read_b128 v[150:153], v158 offset:1024
	ds_read_b128 v[154:157], v158 offset:2048
	ds_read_b128 v[158:161], v158 offset:3072
	s_add_u32 s36, s36, 0x40000
	s_addc_u32 s37, s37, 0
	s_mov_b32 m0, s65
	v_lshl_add_u64 v[228:229], s[36:37], 0, v[162:163]
	ds_read_b128 v[172:175], v189 offset:32768
	ds_read_b128 v[176:179], v189 offset:33792
	ds_read_b128 v[180:183], v189 offset:34816
	ds_read_b128 v[184:187], v189 offset:35840
	ds_read_b128 v[190:193], v189 offset:36864
	ds_read_b128 v[208:211], v189 offset:37888
	ds_read_b128 v[212:215], v189 offset:38912
	ds_read_b128 v[216:219], v189 offset:39936
	global_load_lds_dwordx4 v[228:229], off
	v_lshl_add_u64 v[228:229], s[36:37], 0, v[164:165]
	s_mov_b32 m0, s62
	s_nop 0
	global_load_lds_dwordx4 v[228:229], off
	s_waitcnt vmcnt(8)
	s_waitcnt lgkmcnt(0)
	s_barrier
	s_waitcnt lgkmcnt(0)
	v_mfma_f32_16x16x32_bf16 v[126:129], v[130:133], v[172:175], v[126:129]
	v_mfma_f32_16x16x32_bf16 v[122:125], v[138:141], v[172:175], v[122:125]
	v_mfma_f32_16x16x32_bf16 v[118:121], v[130:133], v[180:183], v[118:121]
	v_mfma_f32_16x16x32_bf16 v[114:117], v[138:141], v[180:183], v[114:117]
	v_mfma_f32_16x16x32_bf16 v[102:105], v[130:133], v[190:193], v[102:105]
	v_mfma_f32_16x16x32_bf16 v[98:101], v[138:141], v[190:193], v[98:101]
	v_mfma_f32_16x16x32_bf16 v[86:89], v[130:133], v[212:215], v[86:89]
	v_mfma_f32_16x16x32_bf16 v[82:85], v[138:141], v[212:215], v[82:85]
	v_mfma_f32_16x16x32_bf16 v[126:129], v[134:137], v[176:179], v[126:129]
	v_mfma_f32_16x16x32_bf16 v[122:125], v[142:145], v[176:179], v[122:125]
	v_mfma_f32_16x16x32_bf16 v[118:121], v[134:137], v[184:187], v[118:121]
	v_mfma_f32_16x16x32_bf16 v[114:117], v[142:145], v[184:187], v[114:117]
	v_mfma_f32_16x16x32_bf16 v[102:105], v[134:137], v[208:211], v[102:105]
	v_mfma_f32_16x16x32_bf16 v[98:101], v[142:145], v[208:211], v[98:101]
	v_mfma_f32_16x16x32_bf16 v[86:89], v[134:137], v[216:219], v[86:89]
	v_mfma_f32_16x16x32_bf16 v[82:85], v[142:145], v[216:219], v[82:85]
	v_mfma_f32_16x16x32_bf16 v[110:113], v[146:149], v[172:175], v[110:113]
	v_mfma_f32_16x16x32_bf16 v[106:109], v[154:157], v[172:175], v[106:109]
	v_mfma_f32_16x16x32_bf16 v[94:97], v[146:149], v[180:183], v[94:97]
	v_mfma_f32_16x16x32_bf16 v[90:93], v[154:157], v[180:183], v[90:93]
	v_mfma_f32_16x16x32_bf16 v[78:81], v[146:149], v[190:193], v[78:81]
	v_mfma_f32_16x16x32_bf16 v[74:77], v[154:157], v[190:193], v[74:77]
	v_mfma_f32_16x16x32_bf16 v[70:73], v[146:149], v[212:215], v[70:73]
	v_mfma_f32_16x16x32_bf16 v[66:69], v[154:157], v[212:215], v[66:69]
	v_mfma_f32_16x16x32_bf16 v[110:113], v[150:153], v[176:179], v[110:113]
	v_mfma_f32_16x16x32_bf16 v[106:109], v[158:161], v[176:179], v[106:109]
	v_mfma_f32_16x16x32_bf16 v[94:97], v[150:153], v[184:187], v[94:97]
	v_mfma_f32_16x16x32_bf16 v[90:93], v[158:161], v[184:187], v[90:93]
	v_mfma_f32_16x16x32_bf16 v[78:81], v[150:153], v[208:211], v[78:81]
	v_mfma_f32_16x16x32_bf16 v[74:77], v[158:161], v[208:211], v[74:77]
	v_mfma_f32_16x16x32_bf16 v[70:73], v[150:153], v[216:219], v[70:73]
	v_mfma_f32_16x16x32_bf16 v[66:69], v[158:161], v[216:219], v[66:69]
	s_barrier
; #define PG8_STAGE(bufoff, gbase, voff) do { _Pragma("unroll") for (int _i = 0; _i < 2; ++_i) \
;         __builtin_amdgcn_global_load_lds((const unsigned*)((const char*)(gbase) + (voff)[_i]), (PG8_LAS unsigned*)(lds + (bufoff) + ldsw + _i * 8192), 16, 0, 0); } while (0)
; #define PG8_LDA(dst, b, h) do { _Pragma("unroll") for (int m = 0; m < 4; ++m) _Pragma("unroll") for (int k = 0; k < 2; ++k) dst[m][k] = *(const PG8_LAS bf16x8*)(lds + PG8_SA(b, h) + aoff + m * 2048 + k * 1024); } while (0)
; #define PG8_MMA(ai, bj, At, Bt) do { __builtin_amdgcn_s_setprio(1); _Pragma("unroll") for (int m = 0; m < 4; ++m) _Pragma("unroll") for (int n = 0; n < 2; ++n) _Pragma("unroll") for (int k = 0; k < 2; ++k) \
;         acc[ai][bj][m][n] = __builtin_amdgcn_mfma_f32_16x16x32_bf16(Bt[n][k], At[m][k], acc[ai][bj][m][n], 0, 0, 0); __builtin_amdgcn_s_setprio(0); } while (0)
; #define PG8_WAIT_V(n) asm volatile("s_waitcnt vmcnt(" #n ")" ::: "memory")
; #define PG8_WAIT_L(n) asm volatile("s_waitcnt lgkmcnt(" #n ")" ::: "memory")
; #define PG8_BAR __builtin_amdgcn_s_barrier()
; #define PG8_SCHED __builtin_amdgcn_sched_barrier(0)
; template <class Epi, class Sched, bool ALIGN_EPI = false, bool SP2 = false>
; __device__ __forceinline__ void gemm_phase(PG8_LAS unsigned char* lds, const Gemm g, const Sched& S, const Epi& E, int wid_in) {
;     ...
;         for (int t = 0; t < nt; t += 2) {
;             const bool last = (t == nt - 2);
;             const char* a1 = cA + (size_t)(t + 1) * kstep;
;             const char* a2 = last ? nA : cA + (size_t)(t + 2) * kstep; const char* b2 = last ? nB : cB + (size_t)(t + 2) * kstep;
;             const char* a3 = a2 + kstep; const char* b3 = b2 + kstep;
;             if (last && has_next) S.a_ready(nxt);
;     ...
;             PG8_LDA(At, 1, 1); PG8_STAGE(PG8_SB(1, 0), b3, voffB); PG8_STAGE(PG8_SB(1, 1), b3 + hstep, voffB); PG8_STAGE(PG8_SA(1, 0), a3, voffA);
;             PG8_WAIT_V(8); PG8_WAIT_L(0); PG8_BAR; PG8_MMA(1, 0, At, B0); PG8_MMA(1, 1, At, B1); PG8_BAR; PG8_SCHED;
	s_add_i32 s36, s40, s59
	v_lshl_add_u64 v[220:221], v[220:221], 0, s[94:95]
	s_mov_b32 m0, s36
	ds_read_b128 v[172:175], v189 offset:49152
	ds_read_b128 v[176:179], v189 offset:50176
	ds_read_b128 v[180:183], v189 offset:51200
	ds_read_b128 v[184:187], v189 offset:52224
	ds_read_b128 v[190:193], v189 offset:53248
	ds_read_b128 v[208:211], v189 offset:54272
	ds_read_b128 v[212:215], v189 offset:55296
	ds_read_b128 v[216:219], v189 offset:56320
	global_load_lds_dwordx4 v[220:221], off
	s_add_i32 m0, s36, 0x2000
	s_add_u32 s34, s34, 0x40080
	v_lshl_add_u64 v[220:221], v[222:223], 0, s[94:95]
	s_addc_u32 s35, s35, 0
	s_add_i32 s36, s41, s59
	global_load_lds_dwordx4 v[220:221], off
	v_lshl_add_u64 v[220:221], s[34:35], 0, v[0:1]
	s_mov_b32 m0, s36
	s_nop 0
	global_load_lds_dwordx4 v[220:221], off
	v_lshl_add_u64 v[220:221], s[34:35], 0, v[166:167]
	s_add_i32 m0, s36, 0x2000
	s_nop 0
	global_load_lds_dwordx4 v[220:221], off
	v_lshl_add_u64 v[220:221], v[224:225], 0, s[94:95]
	s_mov_b32 m0, s88
	s_nop 0
	global_load_lds_dwordx4 v[220:221], off
	v_lshl_add_u64 v[220:221], v[226:227], 0, s[94:95]
	s_mov_b32 m0, s89
	s_nop 0
	global_load_lds_dwordx4 v[220:221], off
	s_waitcnt vmcnt(8)
	s_waitcnt lgkmcnt(0)
	s_barrier
	s_waitcnt lgkmcnt(0)
	v_mfma_f32_16x16x32_bf16 v[62:65], v[130:133], v[172:175], v[62:65]
	v_mfma_f32_16x16x32_bf16 v[58:61], v[138:141], v[172:175], v[58:61]
	v_mfma_f32_16x16x32_bf16 v[54:57], v[130:133], v[180:183], v[54:57]
	v_mfma_f32_16x16x32_bf16 v[50:53], v[138:141], v[180:183], v[50:53]
	v_mfma_f32_16x16x32_bf16 v[38:41], v[130:133], v[190:193], v[38:41]
	v_mfma_f32_16x16x32_bf16 v[34:37], v[138:141], v[190:193], v[34:37]
	v_mfma_f32_16x16x32_bf16 v[22:25], v[130:133], v[212:215], v[22:25]
	v_mfma_f32_16x16x32_bf16 v[18:21], v[138:141], v[212:215], v[18:21]
	v_mfma_f32_16x16x32_bf16 v[62:65], v[134:137], v[176:179], v[62:65]
	v_mfma_f32_16x16x32_bf16 v[58:61], v[142:145], v[176:179], v[58:61]
	v_mfma_f32_16x16x32_bf16 v[54:57], v[134:137], v[184:187], v[54:57]
	v_mfma_f32_16x16x32_bf16 v[50:53], v[142:145], v[184:187], v[50:53]
	v_mfma_f32_16x16x32_bf16 v[38:41], v[134:137], v[208:211], v[38:41]
	v_mfma_f32_16x16x32_bf16 v[34:37], v[142:145], v[208:211], v[34:37]
	v_mfma_f32_16x16x32_bf16 v[22:25], v[134:137], v[216:219], v[22:25]
	v_mfma_f32_16x16x32_bf16 v[18:21], v[142:145], v[216:219], v[18:21]
	v_mfma_f32_16x16x32_bf16 v[46:49], v[146:149], v[172:175], v[46:49]
	v_mfma_f32_16x16x32_bf16 v[42:45], v[154:157], v[172:175], v[42:45]
	v_mfma_f32_16x16x32_bf16 v[30:33], v[146:149], v[180:183], v[30:33]
	v_mfma_f32_16x16x32_bf16 v[26:29], v[154:157], v[180:183], v[26:29]
	v_mfma_f32_16x16x32_bf16 v[14:17], v[146:149], v[190:193], v[14:17]
	v_mfma_f32_16x16x32_bf16 v[10:13], v[154:157], v[190:193], v[10:13]
	v_mfma_f32_16x16x32_bf16 v[6:9], v[146:149], v[212:215], v[6:9]
	v_mfma_f32_16x16x32_bf16 v[2:5], v[154:157], v[212:215], v[2:5]
	v_mfma_f32_16x16x32_bf16 v[46:49], v[150:153], v[176:179], v[46:49]
	v_mfma_f32_16x16x32_bf16 v[42:45], v[158:161], v[176:179], v[42:45]
	v_mfma_f32_16x16x32_bf16 v[30:33], v[150:153], v[184:187], v[30:33]
	v_mfma_f32_16x16x32_bf16 v[26:29], v[158:161], v[184:187], v[26:29]
	v_mfma_f32_16x16x32_bf16 v[14:17], v[150:153], v[208:211], v[14:17]
	v_mfma_f32_16x16x32_bf16 v[10:13], v[158:161], v[208:211], v[10:13]
	v_mfma_f32_16x16x32_bf16 v[6:9], v[150:153], v[216:219], v[6:9]
	v_mfma_f32_16x16x32_bf16 v[2:5], v[158:161], v[216:219], v[2:5]
	s_barrier
	s_add_u32 vcc_hi, vcc_hi, 0x100
	s_addc_u32 s63, s63, 0
	s_add_u32 s30, s30, 0x100
	s_addc_u32 s31, s31, 0
	s_cmp_ge_i32 s56, s1
	s_mov_b32 s34, s56
	s_cbranch_scc0 .LBB0_848
	s_and_b64 vcc, exec, s[12:13]
	s_cbranch_vccz .LBB0_851
	s_barrier

; #define PG8_STAGE(bufoff, gbase, voff) do { _Pragma("unroll") for (int _i = 0; _i < 2; ++_i) \
;         __builtin_amdgcn_global_load_lds((const unsigned*)((const char*)(gbase) + (voff)[_i]), (PG8_LAS unsigned*)(lds + (bufoff) + ldsw + _i * 8192), 16, 0, 0); } while (0)
; #define PG8_LDA(dst, b, h) do { _Pragma("unroll") for (int m = 0; m < 4; ++m) _Pragma("unroll") for (int k = 0; k < 2; ++k) dst[m][k] = *(const PG8_LAS bf16x8*)(lds + PG8_SA(b, h) + aoff + m * 2048 + k * 1024); } while (0)
; #define PG8_LDB(dst, b, h) do { _Pragma("unroll") for (int n = 0; n < 2; ++n) _Pragma("unroll") for (int k = 0; k < 2; ++k) dst[n][k] = *(const PG8_LAS bf16x8*)(lds + PG8_SB(b, h) + boff + n * 2048 + k * 1024); } while (0)
; #define PG8_MMA(ai, bj, At, Bt) do { __builtin_amdgcn_s_setprio(1); _Pragma("unroll") for (int m = 0; m < 4; ++m) _Pragma("unroll") for (int n = 0; n < 2; ++n) _Pragma("unroll") for (int k = 0; k < 2; ++k) \
;         acc[ai][bj][m][n] = __builtin_amdgcn_mfma_f32_16x16x32_bf16(Bt[n][k], At[m][k], acc[ai][bj][m][n], 0, 0, 0); __builtin_amdgcn_s_setprio(0); } while (0)
; #define PG8_WAIT_V(n) asm volatile("s_waitcnt vmcnt(" #n ")" ::: "memory")
; #define PG8_BAR __builtin_amdgcn_s_barrier()
; template <class Epi, class Sched, bool ALIGN_EPI = false, bool SP2 = false>
; __device__ __forceinline__ void gemm_phase(PG8_LAS unsigned char* lds, const Gemm g, const Sched& S, const Epi& E, int wid_in) {
;     ...
;         for (int t = 0; t < nt; t += 2) {
;             const bool last = (t == nt - 2);
;             const char* a1 = cA + (size_t)(t + 1) * kstep;
;             const char* a2 = last ? nA : cA + (size_t)(t + 2) * kstep; const char* b2 = last ? nB : cB + (size_t)(t + 2) * kstep;
;             const char* a3 = a2 + kstep; const char* b3 = b2 + kstep;
;             if (last && has_next) S.a_ready(nxt);
;             if constexpr (SP2) {
;             PG8_LDB(B0, 0, 0); PG8_LDB(B1, 0, 1); PG8_SCHED; PG8_LDA(At, 0, 0); PG8_STAGE(PG8_SA(1, 1), a1 + hstep, voffA);
;             PG8_WAIT_V(8); PG8_WAIT_L(0); PG8_BAR; PG8_MMA(0, 0, At, B0); PG8_MMA(0, 1, At, B1); PG8_BAR; PG8_SCHED;
;             PG8_LDA(At, 0, 1); PG8_STAGE(PG8_SB(0, 0), b2, voffB); PG8_STAGE(PG8_SB(0, 1), b2 + hstep, voffB); PG8_STAGE(PG8_SA(0, 0), a2, voffA);
;             PG8_WAIT_V(8); PG8_WAIT_L(0); PG8_BAR; PG8_MMA(1, 0, At, B0); PG8_MMA(1, 1, At, B1); PG8_BAR; PG8_SCHED;
.LBB0_880:
	s_add_i32 s56, s34, 2
	s_add_u32 s35, s30, 0xfffc0080
	s_addc_u32 s36, s31, -1
	s_add_i32 s40, 0, 0x10000
	s_cmp_eq_u32 vcc_lo, s34
	s_cselect_b32 s37, s15, s36
	s_cselect_b32 s36, s19, s35
	s_cselect_b32 s35, s17, s63
	s_cselect_b32 s34, s27, vcc_hi
	s_add_i32 s42, 0, 0x14000
	v_add_u32_e32 v142, s40, v195
	v_add_u32_e32 v158, s42, v195
	ds_read_b128 v[130:133], v142
	ds_read_b128 v[134:137], v142 offset:1024
	ds_read_b128 v[138:141], v142 offset:2048
	ds_read_b128 v[142:145], v142 offset:3072
	ds_read_b128 v[146:149], v158
	ds_read_b128 v[150:153], v158 offset:1024
	ds_read_b128 v[154:157], v158 offset:2048
	ds_read_b128 v[158:161], v158 offset:3072
	v_lshl_add_u64 v[218:219], s[30:31], 0, v[216:217]
	s_add_i32 m0, s29, 0xc000
	ds_read_b128 v[162:165], v251
	ds_read_b128 v[166:169], v251 offset:1024
	ds_read_b128 v[170:173], v251 offset:2048
	ds_read_b128 v[174:177], v251 offset:3072
	ds_read_b128 v[178:181], v251 offset:4096
	ds_read_b128 v[182:185], v251 offset:5120
	ds_read_b128 v[186:189], v251 offset:6144
	ds_read_b128 v[190:193], v251 offset:7168
	global_load_lds_dwordx4 v[218:219], off
	v_lshl_add_u64 v[218:219], s[30:31], 0, v[214:215]
	s_add_i32 m0, s29, 0xe000
	s_nop 0
	global_load_lds_dwordx4 v[218:219], off
	s_waitcnt vmcnt(8)
	s_waitcnt lgkmcnt(0)
	s_barrier
	s_waitcnt lgkmcnt(0)
	v_mfma_f32_16x16x32_bf16 v[126:129], v[130:133], v[162:165], v[126:129]
	v_mfma_f32_16x16x32_bf16 v[122:125], v[138:141], v[162:165], v[122:125]
	v_mfma_f32_16x16x32_bf16 v[118:121], v[130:133], v[170:173], v[118:121]
	v_mfma_f32_16x16x32_bf16 v[114:117], v[138:141], v[170:173], v[114:117]
	v_mfma_f32_16x16x32_bf16 v[102:105], v[130:133], v[178:181], v[102:105]
	v_mfma_f32_16x16x32_bf16 v[98:101], v[138:141], v[178:181], v[98:101]
	v_mfma_f32_16x16x32_bf16 v[86:89], v[130:133], v[186:189], v[86:89]
	v_mfma_f32_16x16x32_bf16 v[82:85], v[138:141], v[186:189], v[82:85]
	v_mfma_f32_16x16x32_bf16 v[126:129], v[134:137], v[166:169], v[126:129]
	v_mfma_f32_16x16x32_bf16 v[122:125], v[142:145], v[166:169], v[122:125]
	v_mfma_f32_16x16x32_bf16 v[118:121], v[134:137], v[174:177], v[118:121]
	v_mfma_f32_16x16x32_bf16 v[114:117], v[142:145], v[174:177], v[114:117]
	v_mfma_f32_16x16x32_bf16 v[102:105], v[134:137], v[182:185], v[102:105]
	v_mfma_f32_16x16x32_bf16 v[98:101], v[142:145], v[182:185], v[98:101]
	v_mfma_f32_16x16x32_bf16 v[86:89], v[134:137], v[190:193], v[86:89]
	v_mfma_f32_16x16x32_bf16 v[82:85], v[142:145], v[190:193], v[82:85]
	v_mfma_f32_16x16x32_bf16 v[110:113], v[146:149], v[162:165], v[110:113]
	v_mfma_f32_16x16x32_bf16 v[106:109], v[154:157], v[162:165], v[106:109]
	v_mfma_f32_16x16x32_bf16 v[94:97], v[146:149], v[170:173], v[94:97]
	v_mfma_f32_16x16x32_bf16 v[90:93], v[154:157], v[170:173], v[90:93]
	v_mfma_f32_16x16x32_bf16 v[78:81], v[146:149], v[178:181], v[78:81]
	v_mfma_f32_16x16x32_bf16 v[74:77], v[154:157], v[178:181], v[74:77]
	v_mfma_f32_16x16x32_bf16 v[70:73], v[146:149], v[186:189], v[70:73]
	v_mfma_f32_16x16x32_bf16 v[66:69], v[154:157], v[186:189], v[66:69]
	v_mfma_f32_16x16x32_bf16 v[110:113], v[150:153], v[166:169], v[110:113]
	v_mfma_f32_16x16x32_bf16 v[106:109], v[158:161], v[166:169], v[106:109]
	v_mfma_f32_16x16x32_bf16 v[94:97], v[150:153], v[174:177], v[94:97]
	v_mfma_f32_16x16x32_bf16 v[90:93], v[158:161], v[174:177], v[90:93]
	v_mfma_f32_16x16x32_bf16 v[78:81], v[150:153], v[182:185], v[78:81]
	v_mfma_f32_16x16x32_bf16 v[74:77], v[158:161], v[182:185], v[74:77]
	v_mfma_f32_16x16x32_bf16 v[70:73], v[150:153], v[190:193], v[70:73]
	v_mfma_f32_16x16x32_bf16 v[66:69], v[158:161], v[190:193], v[66:69]
	s_barrier
	s_add_i32 s40, s40, s59
	v_lshl_add_u64 v[218:219], s[34:35], 0, v[0:1]
	s_mov_b32 m0, s40
	ds_read_b128 v[162:165], v251 offset:16384
	ds_read_b128 v[166:169], v251 offset:17408
	ds_read_b128 v[170:173], v251 offset:18432
	ds_read_b128 v[174:177], v251 offset:19456
	ds_read_b128 v[178:181], v251 offset:20480
	ds_read_b128 v[182:185], v251 offset:21504
	ds_read_b128 v[186:189], v251 offset:22528
	ds_read_b128 v[190:193], v251 offset:23552
	global_load_lds_dwordx4 v[218:219], off
	s_add_i32 m0, s40, 0x2000
	s_add_u32 s40, s34, 0x40000
	v_lshl_add_u64 v[220:221], s[34:35], 0, v[212:213]
	s_addc_u32 s41, s35, 0
	s_add_i32 s42, s42, s59
	global_load_lds_dwordx4 v[220:221], off
	v_lshl_add_u64 v[222:223], s[40:41], 0, v[0:1]
	s_mov_b32 m0, s42
	v_lshl_add_u64 v[224:225], s[36:37], 0, v[210:211]
	global_load_lds_dwordx4 v[222:223], off
	v_lshl_add_u64 v[222:223], s[40:41], 0, v[212:213]
	s_add_i32 m0, s42, 0x2000
	s_nop 0
	global_load_lds_dwordx4 v[222:223], off
	v_lshl_add_u64 v[222:223], s[36:37], 0, v[208:209]
	s_mov_b32 m0, s29
	s_nop 0
	global_load_lds_dwordx4 v[222:223], off
	s_mov_b32 m0, s48
	s_nop 0
	global_load_lds_dwordx4 v[224:225], off
	s_waitcnt vmcnt(8)
	s_waitcnt lgkmcnt(0)
	s_barrier
; #define PG8_STAGE(bufoff, gbase, voff) do { _Pragma("unroll") for (int _i = 0; _i < 2; ++_i) \
;         __builtin_amdgcn_global_load_lds((const unsigned*)((const char*)(gbase) + (voff)[_i]), (PG8_LAS unsigned*)(lds + (bufoff) + ldsw + _i * 8192), 16, 0, 0); } while (0)
; #define PG8_LDA(dst, b, h) do { _Pragma("unroll") for (int m = 0; m < 4; ++m) _Pragma("unroll") for (int k = 0; k < 2; ++k) dst[m][k] = *(const PG8_LAS bf16x8*)(lds + PG8_SA(b, h) + aoff + m * 2048 + k * 1024); } while (0)
; #define PG8_LDB(dst, b, h) do { _Pragma("unroll") for (int n = 0; n < 2; ++n) _Pragma("unroll") for (int k = 0; k < 2; ++k) dst[n][k] = *(const PG8_LAS bf16x8*)(lds + PG8_SB(b, h) + boff + n * 2048 + k * 1024); } while (0)
; #define PG8_MMA(ai, bj, At, Bt) do { __builtin_amdgcn_s_setprio(1); _Pragma("unroll") for (int m = 0; m < 4; ++m) _Pragma("unroll") for (int n = 0; n < 2; ++n) _Pragma("unroll") for (int k = 0; k < 2; ++k) \
;         acc[ai][bj][m][n] = __builtin_amdgcn_mfma_f32_16x16x32_bf16(Bt[n][k], At[m][k], acc[ai][bj][m][n], 0, 0, 0); __builtin_amdgcn_s_setprio(0); } while (0)
; #define PG8_WAIT_V(n) asm volatile("s_waitcnt vmcnt(" #n ")" ::: "memory")
; #define PG8_WAIT_L(n) asm volatile("s_waitcnt lgkmcnt(" #n ")" ::: "memory")
; #define PG8_BAR __builtin_amdgcn_s_barrier()
; #define PG8_SCHED __builtin_amdgcn_sched_barrier(0)
; template <class Epi, class Sched, bool ALIGN_EPI = false, bool SP2 = false>
; __device__ __forceinline__ void gemm_phase(PG8_LAS unsigned char* lds, const Gemm g, const Sched& S, const Epi& E, int wid_in) {
;     ...
;             PG8_WAIT_V(8); PG8_WAIT_L(0); PG8_BAR; PG8_MMA(1, 0, At, B0); PG8_MMA(1, 1, At, B1); PG8_BAR; PG8_SCHED;
;             PG8_LDB(B0, 1, 0); PG8_LDB(B1, 1, 1); PG8_SCHED; PG8_LDA(At, 1, 0); PG8_STAGE(PG8_SA(0, 1), a2 + hstep, voffA);
;             PG8_WAIT_V(8); PG8_WAIT_L(0); PG8_BAR; PG8_MMA(0, 0, At, B0); PG8_MMA(0, 1, At, B1); PG8_BAR; PG8_SCHED;
	s_waitcnt lgkmcnt(0)
	v_mfma_f32_16x16x32_bf16 v[62:65], v[130:133], v[162:165], v[62:65]
	v_mfma_f32_16x16x32_bf16 v[58:61], v[138:141], v[162:165], v[58:61]
	v_mfma_f32_16x16x32_bf16 v[54:57], v[130:133], v[170:173], v[54:57]
	v_mfma_f32_16x16x32_bf16 v[50:53], v[138:141], v[170:173], v[50:53]
	v_mfma_f32_16x16x32_bf16 v[38:41], v[130:133], v[178:181], v[38:41]
	v_mfma_f32_16x16x32_bf16 v[34:37], v[138:141], v[178:181], v[34:37]
	v_mfma_f32_16x16x32_bf16 v[22:25], v[130:133], v[186:189], v[22:25]
	v_mfma_f32_16x16x32_bf16 v[18:21], v[138:141], v[186:189], v[18:21]
	v_mfma_f32_16x16x32_bf16 v[62:65], v[134:137], v[166:169], v[62:65]
	v_mfma_f32_16x16x32_bf16 v[58:61], v[142:145], v[166:169], v[58:61]
	v_mfma_f32_16x16x32_bf16 v[54:57], v[134:137], v[174:177], v[54:57]
	v_mfma_f32_16x16x32_bf16 v[50:53], v[142:145], v[174:177], v[50:53]
	v_mfma_f32_16x16x32_bf16 v[38:41], v[134:137], v[182:185], v[38:41]
	v_mfma_f32_16x16x32_bf16 v[34:37], v[142:145], v[182:185], v[34:37]
	v_mfma_f32_16x16x32_bf16 v[22:25], v[134:137], v[190:193], v[22:25]
	v_mfma_f32_16x16x32_bf16 v[18:21], v[142:145], v[190:193], v[18:21]
	v_mfma_f32_16x16x32_bf16 v[46:49], v[146:149], v[162:165], v[46:49]
	v_mfma_f32_16x16x32_bf16 v[42:45], v[154:157], v[162:165], v[42:45]
	v_mfma_f32_16x16x32_bf16 v[30:33], v[146:149], v[170:173], v[30:33]
	v_mfma_f32_16x16x32_bf16 v[26:29], v[154:157], v[170:173], v[26:29]
	v_mfma_f32_16x16x32_bf16 v[14:17], v[146:149], v[178:181], v[14:17]
	v_mfma_f32_16x16x32_bf16 v[10:13], v[154:157], v[178:181], v[10:13]
	v_mfma_f32_16x16x32_bf16 v[6:9], v[146:149], v[186:189], v[6:9]
	v_mfma_f32_16x16x32_bf16 v[2:5], v[154:157], v[186:189], v[2:5]
	v_mfma_f32_16x16x32_bf16 v[46:49], v[150:153], v[166:169], v[46:49]
	v_mfma_f32_16x16x32_bf16 v[42:45], v[158:161], v[166:169], v[42:45]
	v_mfma_f32_16x16x32_bf16 v[30:33], v[150:153], v[174:177], v[30:33]
	v_mfma_f32_16x16x32_bf16 v[26:29], v[158:161], v[174:177], v[26:29]
	v_mfma_f32_16x16x32_bf16 v[14:17], v[150:153], v[182:185], v[14:17]
	v_mfma_f32_16x16x32_bf16 v[10:13], v[158:161], v[182:185], v[10:13]
	v_mfma_f32_16x16x32_bf16 v[6:9], v[150:153], v[190:193], v[6:9]
	v_mfma_f32_16x16x32_bf16 v[2:5], v[158:161], v[190:193], v[2:5]
	s_barrier
	s_add_i32 s40, 0, 0x18000
	s_add_i32 s41, 0, 0x1c000
	v_add_u32_e32 v142, s40, v195
	v_add_u32_e32 v158, s41, v195
	ds_read_b128 v[130:133], v142
	ds_read_b128 v[134:137], v142 offset:1024
	ds_read_b128 v[138:141], v142 offset:2048
	ds_read_b128 v[142:145], v142 offset:3072
	ds_read_b128 v[146:149], v158
	ds_read_b128 v[150:153], v158 offset:1024
	ds_read_b128 v[154:157], v158 offset:2048
	ds_read_b128 v[158:161], v158 offset:3072
	s_add_u32 s36, s36, 0x40000
	s_addc_u32 s37, s37, 0
	s_mov_b32 m0, s61
	v_lshl_add_u64 v[226:227], s[36:37], 0, v[208:209]
	ds_read_b128 v[162:165], v251 offset:32768
	ds_read_b128 v[166:169], v251 offset:33792
	ds_read_b128 v[170:173], v251 offset:34816
	ds_read_b128 v[174:177], v251 offset:35840
	ds_read_b128 v[178:181], v251 offset:36864
	ds_read_b128 v[182:185], v251 offset:37888
	ds_read_b128 v[186:189], v251 offset:38912
	ds_read_b128 v[190:193], v251 offset:39936
	global_load_lds_dwordx4 v[226:227], off
	v_lshl_add_u64 v[226:227], s[36:37], 0, v[210:211]
	s_mov_b32 m0, s62
	s_nop 0
	global_load_lds_dwordx4 v[226:227], off
	s_waitcnt vmcnt(8)
	s_waitcnt lgkmcnt(0)
	s_barrier
	s_waitcnt lgkmcnt(0)
	v_mfma_f32_16x16x32_bf16 v[126:129], v[130:133], v[162:165], v[126:129]
	v_mfma_f32_16x16x32_bf16 v[122:125], v[138:141], v[162:165], v[122:125]
	v_mfma_f32_16x16x32_bf16 v[118:121], v[130:133], v[170:173], v[118:121]
	v_mfma_f32_16x16x32_bf16 v[114:117], v[138:141], v[170:173], v[114:117]
	v_mfma_f32_16x16x32_bf16 v[102:105], v[130:133], v[178:181], v[102:105]
	v_mfma_f32_16x16x32_bf16 v[98:101], v[138:141], v[178:181], v[98:101]
	v_mfma_f32_16x16x32_bf16 v[86:89], v[130:133], v[186:189], v[86:89]
	v_mfma_f32_16x16x32_bf16 v[82:85], v[138:141], v[186:189], v[82:85]
	v_mfma_f32_16x16x32_bf16 v[126:129], v[134:137], v[166:169], v[126:129]
	v_mfma_f32_16x16x32_bf16 v[122:125], v[142:145], v[166:169], v[122:125]
	v_mfma_f32_16x16x32_bf16 v[118:121], v[134:137], v[174:177], v[118:121]
	v_mfma_f32_16x16x32_bf16 v[114:117], v[142:145], v[174:177], v[114:117]
	v_mfma_f32_16x16x32_bf16 v[102:105], v[134:137], v[182:185], v[102:105]
	v_mfma_f32_16x16x32_bf16 v[98:101], v[142:145], v[182:185], v[98:101]
	v_mfma_f32_16x16x32_bf16 v[86:89], v[134:137], v[190:193], v[86:89]
	v_mfma_f32_16x16x32_bf16 v[82:85], v[142:145], v[190:193], v[82:85]
	v_mfma_f32_16x16x32_bf16 v[110:113], v[146:149], v[162:165], v[110:113]
	v_mfma_f32_16x16x32_bf16 v[106:109], v[154:157], v[162:165], v[106:109]
	v_mfma_f32_16x16x32_bf16 v[94:97], v[146:149], v[170:173], v[94:97]
	v_mfma_f32_16x16x32_bf16 v[90:93], v[154:157], v[170:173], v[90:93]
	v_mfma_f32_16x16x32_bf16 v[78:81], v[146:149], v[178:181], v[78:81]
	v_mfma_f32_16x16x32_bf16 v[74:77], v[154:157], v[178:181], v[74:77]
	v_mfma_f32_16x16x32_bf16 v[70:73], v[146:149], v[186:189], v[70:73]
	v_mfma_f32_16x16x32_bf16 v[66:69], v[154:157], v[186:189], v[66:69]
	v_mfma_f32_16x16x32_bf16 v[110:113], v[150:153], v[166:169], v[110:113]
	v_mfma_f32_16x16x32_bf16 v[106:109], v[158:161], v[166:169], v[106:109]
	v_mfma_f32_16x16x32_bf16 v[94:97], v[150:153], v[174:177], v[94:97]
	v_mfma_f32_16x16x32_bf16 v[90:93], v[158:161], v[174:177], v[90:93]
	v_mfma_f32_16x16x32_bf16 v[78:81], v[150:153], v[182:185], v[78:81]
	v_mfma_f32_16x16x32_bf16 v[74:77], v[158:161], v[182:185], v[74:77]
	v_mfma_f32_16x16x32_bf16 v[70:73], v[150:153], v[190:193], v[70:73]
	v_mfma_f32_16x16x32_bf16 v[66:69], v[158:161], v[190:193], v[66:69]
	s_barrier
; #define PG8_STAGE(bufoff, gbase, voff) do { _Pragma("unroll") for (int _i = 0; _i < 2; ++_i) \
;         __builtin_amdgcn_global_load_lds((const unsigned*)((const char*)(gbase) + (voff)[_i]), (PG8_LAS unsigned*)(lds + (bufoff) + ldsw + _i * 8192), 16, 0, 0); } while (0)
; #define PG8_LDA(dst, b, h) do { _Pragma("unroll") for (int m = 0; m < 4; ++m) _Pragma("unroll") for (int k = 0; k < 2; ++k) dst[m][k] = *(const PG8_LAS bf16x8*)(lds + PG8_SA(b, h) + aoff + m * 2048 + k * 1024); } while (0)
; #define PG8_MMA(ai, bj, At, Bt) do { __builtin_amdgcn_s_setprio(1); _Pragma("unroll") for (int m = 0; m < 4; ++m) _Pragma("unroll") for (int n = 0; n < 2; ++n) _Pragma("unroll") for (int k = 0; k < 2; ++k) \
;         acc[ai][bj][m][n] = __builtin_amdgcn_mfma_f32_16x16x32_bf16(Bt[n][k], At[m][k], acc[ai][bj][m][n], 0, 0, 0); __builtin_amdgcn_s_setprio(0); } while (0)
; #define PG8_WAIT_V(n) asm volatile("s_waitcnt vmcnt(" #n ")" ::: "memory")
; #define PG8_WAIT_L(n) asm volatile("s_waitcnt lgkmcnt(" #n ")" ::: "memory")
; #define PG8_BAR __builtin_amdgcn_s_barrier()
; #define PG8_SCHED __builtin_amdgcn_sched_barrier(0)
; template <class Epi, class Sched, bool ALIGN_EPI = false, bool SP2 = false>
; __device__ __forceinline__ void gemm_phase(PG8_LAS unsigned char* lds, const Gemm g, const Sched& S, const Epi& E, int wid_in) {
;     ...
;         for (int t = 0; t < nt; t += 2) {
;             const bool last = (t == nt - 2);
;             const char* a1 = cA + (size_t)(t + 1) * kstep;
;             const char* a2 = last ? nA : cA + (size_t)(t + 2) * kstep; const char* b2 = last ? nB : cB + (size_t)(t + 2) * kstep;
;     ...
;             PG8_LDA(At, 1, 1); PG8_STAGE(PG8_SB(1, 0), b3, voffB); PG8_STAGE(PG8_SB(1, 1), b3 + hstep, voffB); PG8_STAGE(PG8_SA(1, 0), a3, voffA);
;             PG8_WAIT_V(8); PG8_WAIT_L(0); PG8_BAR; PG8_MMA(1, 0, At, B0); PG8_MMA(1, 1, At, B1); PG8_BAR; PG8_SCHED;
	s_add_i32 s36, s40, s59
	v_lshl_add_u64 v[218:219], v[218:219], 0, s[94:95]
	s_mov_b32 m0, s36
	ds_read_b128 v[162:165], v251 offset:49152
	ds_read_b128 v[166:169], v251 offset:50176
	ds_read_b128 v[170:173], v251 offset:51200
	ds_read_b128 v[174:177], v251 offset:52224
	ds_read_b128 v[178:181], v251 offset:53248
	ds_read_b128 v[182:185], v251 offset:54272
	ds_read_b128 v[186:189], v251 offset:55296
	ds_read_b128 v[190:193], v251 offset:56320
	global_load_lds_dwordx4 v[218:219], off
	s_add_i32 m0, s36, 0x2000
	s_add_u32 s34, s34, 0x40080
	v_lshl_add_u64 v[218:219], v[220:221], 0, s[94:95]
	s_addc_u32 s35, s35, 0
	s_add_i32 s36, s41, s59
	global_load_lds_dwordx4 v[218:219], off
	v_lshl_add_u64 v[218:219], s[34:35], 0, v[0:1]
	s_mov_b32 m0, s36
	s_nop 0
	global_load_lds_dwordx4 v[218:219], off
	v_lshl_add_u64 v[218:219], s[34:35], 0, v[212:213]
	s_add_i32 m0, s36, 0x2000
	s_nop 0
	global_load_lds_dwordx4 v[218:219], off
	v_lshl_add_u64 v[218:219], v[222:223], 0, s[94:95]
	s_mov_b32 m0, s89
	s_nop 0
	global_load_lds_dwordx4 v[218:219], off
	v_lshl_add_u64 v[218:219], v[224:225], 0, s[94:95]
	s_mov_b32 m0, s90
	s_nop 0
	global_load_lds_dwordx4 v[218:219], off
	s_waitcnt vmcnt(8)
	s_waitcnt lgkmcnt(0)
	s_barrier
	s_waitcnt lgkmcnt(0)
	v_mfma_f32_16x16x32_bf16 v[62:65], v[130:133], v[162:165], v[62:65]
	v_mfma_f32_16x16x32_bf16 v[58:61], v[138:141], v[162:165], v[58:61]
	v_mfma_f32_16x16x32_bf16 v[54:57], v[130:133], v[170:173], v[54:57]
	v_mfma_f32_16x16x32_bf16 v[50:53], v[138:141], v[170:173], v[50:53]
	v_mfma_f32_16x16x32_bf16 v[38:41], v[130:133], v[178:181], v[38:41]
	v_mfma_f32_16x16x32_bf16 v[34:37], v[138:141], v[178:181], v[34:37]
	v_mfma_f32_16x16x32_bf16 v[22:25], v[130:133], v[186:189], v[22:25]
	v_mfma_f32_16x16x32_bf16 v[18:21], v[138:141], v[186:189], v[18:21]
	v_mfma_f32_16x16x32_bf16 v[62:65], v[134:137], v[166:169], v[62:65]
	v_mfma_f32_16x16x32_bf16 v[58:61], v[142:145], v[166:169], v[58:61]
	v_mfma_f32_16x16x32_bf16 v[54:57], v[134:137], v[174:177], v[54:57]
	v_mfma_f32_16x16x32_bf16 v[50:53], v[142:145], v[174:177], v[50:53]
	v_mfma_f32_16x16x32_bf16 v[38:41], v[134:137], v[182:185], v[38:41]
	v_mfma_f32_16x16x32_bf16 v[34:37], v[142:145], v[182:185], v[34:37]
	v_mfma_f32_16x16x32_bf16 v[22:25], v[134:137], v[190:193], v[22:25]
	v_mfma_f32_16x16x32_bf16 v[18:21], v[142:145], v[190:193], v[18:21]
	v_mfma_f32_16x16x32_bf16 v[46:49], v[146:149], v[162:165], v[46:49]
	v_mfma_f32_16x16x32_bf16 v[42:45], v[154:157], v[162:165], v[42:45]
	v_mfma_f32_16x16x32_bf16 v[30:33], v[146:149], v[170:173], v[30:33]
	v_mfma_f32_16x16x32_bf16 v[26:29], v[154:157], v[170:173], v[26:29]
	v_mfma_f32_16x16x32_bf16 v[14:17], v[146:149], v[178:181], v[14:17]
	v_mfma_f32_16x16x32_bf16 v[10:13], v[154:157], v[178:181], v[10:13]
	v_mfma_f32_16x16x32_bf16 v[6:9], v[146:149], v[186:189], v[6:9]
	v_mfma_f32_16x16x32_bf16 v[2:5], v[154:157], v[186:189], v[2:5]
	v_mfma_f32_16x16x32_bf16 v[46:49], v[150:153], v[166:169], v[46:49]
	v_mfma_f32_16x16x32_bf16 v[42:45], v[158:161], v[166:169], v[42:45]
	v_mfma_f32_16x16x32_bf16 v[30:33], v[150:153], v[174:177], v[30:33]
	v_mfma_f32_16x16x32_bf16 v[26:29], v[158:161], v[174:177], v[26:29]
	v_mfma_f32_16x16x32_bf16 v[14:17], v[150:153], v[182:185], v[14:17]
	v_mfma_f32_16x16x32_bf16 v[10:13], v[158:161], v[182:185], v[10:13]
	v_mfma_f32_16x16x32_bf16 v[6:9], v[150:153], v[190:193], v[6:9]
	v_mfma_f32_16x16x32_bf16 v[2:5], v[158:161], v[190:193], v[2:5]
	s_barrier
	s_add_u32 vcc_hi, vcc_hi, 0x100
	s_addc_u32 s63, s63, 0
	s_add_u32 s30, s30, 0x100
	s_addc_u32 s31, s31, 0
	s_cmp_ge_i32 s56, s1
	s_mov_b32 s34, s56
	s_cbranch_scc0 .LBB0_880
	s_and_b64 vcc, exec, s[12:13]
	s_cbranch_vccz .LBB0_883
	s_barrier

; #define PG8_STAGE(bufoff, gbase, voff) do { _Pragma("unroll") for (int _i = 0; _i < 2; ++_i) \
;         __builtin_amdgcn_global_load_lds((const unsigned*)((const char*)(gbase) + (voff)[_i]), (PG8_LAS unsigned*)(lds + (bufoff) + ldsw + _i * 8192), 16, 0, 0); } while (0)
; #define PG8_LDA(dst, b, h) do { _Pragma("unroll") for (int m = 0; m < 4; ++m) _Pragma("unroll") for (int k = 0; k < 2; ++k) dst[m][k] = *(const PG8_LAS bf16x8*)(lds + PG8_SA(b, h) + aoff + m * 2048 + k * 1024); } while (0)
; #define PG8_LDB(dst, b, h) do { _Pragma("unroll") for (int n = 0; n < 2; ++n) _Pragma("unroll") for (int k = 0; k < 2; ++k) dst[n][k] = *(const PG8_LAS bf16x8*)(lds + PG8_SB(b, h) + boff + n * 2048 + k * 1024); } while (0)
; #define PG8_MMA(ai, bj, At, Bt) do { __builtin_amdgcn_s_setprio(1); _Pragma("unroll") for (int m = 0; m < 4; ++m) _Pragma("unroll") for (int n = 0; n < 2; ++n) _Pragma("unroll") for (int k = 0; k < 2; ++k) \
;         acc[ai][bj][m][n] = __builtin_amdgcn_mfma_f32_16x16x32_bf16(Bt[n][k], At[m][k], acc[ai][bj][m][n], 0, 0, 0); __builtin_amdgcn_s_setprio(0); } while (0)
; #define PG8_WAIT_V(n) asm volatile("s_waitcnt vmcnt(" #n ")" ::: "memory")
; #define PG8_BAR __builtin_amdgcn_s_barrier()
; template <class Epi, class Sched, bool ALIGN_EPI = false, bool SP2 = false>
; __device__ __forceinline__ void gemm_phase(PG8_LAS unsigned char* lds, const Gemm g, const Sched& S, const Epi& E, int wid_in) {
;     ...
;         for (int t = 0; t < nt; t += 2) {
;             const bool last = (t == nt - 2);
;             const char* a1 = cA + (size_t)(t + 1) * kstep;
;             const char* a2 = last ? nA : cA + (size_t)(t + 2) * kstep; const char* b2 = last ? nB : cB + (size_t)(t + 2) * kstep;
;             const char* a3 = a2 + kstep; const char* b3 = b2 + kstep;
;             if (last && has_next) S.a_ready(nxt);
;             if constexpr (SP2) {
;             PG8_LDB(B0, 0, 0); PG8_LDB(B1, 0, 1); PG8_SCHED; PG8_LDA(At, 0, 0); PG8_STAGE(PG8_SA(1, 1), a1 + hstep, voffA);
;             PG8_WAIT_V(8); PG8_WAIT_L(0); PG8_BAR; PG8_MMA(0, 0, At, B0); PG8_MMA(0, 1, At, B1); PG8_BAR; PG8_SCHED;
;             PG8_LDA(At, 0, 1); PG8_STAGE(PG8_SB(0, 0), b2, voffB); PG8_STAGE(PG8_SB(0, 1), b2 + hstep, voffB); PG8_STAGE(PG8_SA(0, 0), a2, voffA);
;             PG8_WAIT_V(8); PG8_WAIT_L(0); PG8_BAR; PG8_MMA(1, 0, At, B0); PG8_MMA(1, 1, At, B1); PG8_BAR; PG8_SCHED;
.LBB0_1021:
	s_add_i32 s56, s27, 2
	s_add_u32 s34, s30, 0xfff80080
	s_addc_u32 s35, s31, -1
	s_add_i32 s40, 0, 0x10000
	s_cmp_eq_u32 s17, s27
	s_cselect_b32 s37, s23, s35
	s_cselect_b32 s36, s22, s34
	s_cselect_b32 s35, s25, s21
	s_cselect_b32 s34, s24, s19
	s_add_i32 s27, 0, 0x14000
	v_add_u32_e32 v142, s40, v176
	v_add_u32_e32 v168, s27, v176
	ds_read_b128 v[130:133], v142
	ds_read_b128 v[134:137], v142 offset:1024
	ds_read_b128 v[138:141], v142 offset:2048
	ds_read_b128 v[142:145], v142 offset:3072
	ds_read_b128 v[146:149], v168
	ds_read_b128 v[160:163], v168 offset:1024
	ds_read_b128 v[164:167], v168 offset:2048
	ds_read_b128 v[168:171], v168 offset:3072
	v_lshl_add_u64 v[220:221], s[30:31], 0, v[158:159]
	s_add_i32 m0, s29, 0xc000
	ds_read_b128 v[172:175], v177
	ds_read_b128 v[178:181], v177 offset:1024
	ds_read_b128 v[182:185], v177 offset:2048
	ds_read_b128 v[186:189], v177 offset:3072
	ds_read_b128 v[190:193], v177 offset:4096
	ds_read_b128 v[208:211], v177 offset:5120
	ds_read_b128 v[212:215], v177 offset:6144
	ds_read_b128 v[216:219], v177 offset:7168
	global_load_lds_dwordx4 v[220:221], off
	v_lshl_add_u64 v[220:221], s[30:31], 0, v[156:157]
	s_add_i32 m0, s29, 0xe000
	s_nop 0
	global_load_lds_dwordx4 v[220:221], off
	s_waitcnt vmcnt(8)
	s_waitcnt lgkmcnt(0)
	s_barrier
	s_waitcnt lgkmcnt(0)
	v_mfma_f32_16x16x32_bf16 v[126:129], v[130:133], v[172:175], v[126:129]
	v_mfma_f32_16x16x32_bf16 v[122:125], v[138:141], v[172:175], v[122:125]
	v_mfma_f32_16x16x32_bf16 v[118:121], v[130:133], v[182:185], v[118:121]
	v_mfma_f32_16x16x32_bf16 v[114:117], v[138:141], v[182:185], v[114:117]
	v_mfma_f32_16x16x32_bf16 v[102:105], v[130:133], v[190:193], v[102:105]
	v_mfma_f32_16x16x32_bf16 v[98:101], v[138:141], v[190:193], v[98:101]
	v_mfma_f32_16x16x32_bf16 v[86:89], v[130:133], v[212:215], v[86:89]
	v_mfma_f32_16x16x32_bf16 v[82:85], v[138:141], v[212:215], v[82:85]
	v_mfma_f32_16x16x32_bf16 v[126:129], v[134:137], v[178:181], v[126:129]
	v_mfma_f32_16x16x32_bf16 v[122:125], v[142:145], v[178:181], v[122:125]
	v_mfma_f32_16x16x32_bf16 v[118:121], v[134:137], v[186:189], v[118:121]
	v_mfma_f32_16x16x32_bf16 v[114:117], v[142:145], v[186:189], v[114:117]
	v_mfma_f32_16x16x32_bf16 v[102:105], v[134:137], v[208:211], v[102:105]
	v_mfma_f32_16x16x32_bf16 v[98:101], v[142:145], v[208:211], v[98:101]
	v_mfma_f32_16x16x32_bf16 v[86:89], v[134:137], v[216:219], v[86:89]
	v_mfma_f32_16x16x32_bf16 v[82:85], v[142:145], v[216:219], v[82:85]
	v_mfma_f32_16x16x32_bf16 v[110:113], v[146:149], v[172:175], v[110:113]
	v_mfma_f32_16x16x32_bf16 v[106:109], v[164:167], v[172:175], v[106:109]
	v_mfma_f32_16x16x32_bf16 v[94:97], v[146:149], v[182:185], v[94:97]
	v_mfma_f32_16x16x32_bf16 v[90:93], v[164:167], v[182:185], v[90:93]
	v_mfma_f32_16x16x32_bf16 v[78:81], v[146:149], v[190:193], v[78:81]
	v_mfma_f32_16x16x32_bf16 v[74:77], v[164:167], v[190:193], v[74:77]
	v_mfma_f32_16x16x32_bf16 v[70:73], v[146:149], v[212:215], v[70:73]
	v_mfma_f32_16x16x32_bf16 v[66:69], v[164:167], v[212:215], v[66:69]
	v_mfma_f32_16x16x32_bf16 v[110:113], v[160:163], v[178:181], v[110:113]
	v_mfma_f32_16x16x32_bf16 v[106:109], v[168:171], v[178:181], v[106:109]
	v_mfma_f32_16x16x32_bf16 v[94:97], v[160:163], v[186:189], v[94:97]
	v_mfma_f32_16x16x32_bf16 v[90:93], v[168:171], v[186:189], v[90:93]
	v_mfma_f32_16x16x32_bf16 v[78:81], v[160:163], v[208:211], v[78:81]
	v_mfma_f32_16x16x32_bf16 v[74:77], v[168:171], v[208:211], v[74:77]
	v_mfma_f32_16x16x32_bf16 v[70:73], v[160:163], v[216:219], v[70:73]
	v_mfma_f32_16x16x32_bf16 v[66:69], v[168:171], v[216:219], v[66:69]
	s_barrier
	s_add_i32 s40, s40, s59
	v_lshl_add_u64 v[220:221], s[34:35], 0, v[0:1]
	s_mov_b32 m0, s40
	ds_read_b128 v[172:175], v177 offset:16384
	ds_read_b128 v[178:181], v177 offset:17408
	ds_read_b128 v[182:185], v177 offset:18432
	ds_read_b128 v[186:189], v177 offset:19456
	ds_read_b128 v[190:193], v177 offset:20480
	ds_read_b128 v[208:211], v177 offset:21504
	ds_read_b128 v[212:215], v177 offset:22528
	ds_read_b128 v[216:219], v177 offset:23552
	global_load_lds_dwordx4 v[220:221], off
	s_add_i32 m0, s40, 0x2000
	s_add_u32 s40, s34, 0x80000
	v_lshl_add_u64 v[222:223], s[34:35], 0, v[154:155]
	s_addc_u32 s41, s35, 0
	s_add_i32 s27, s27, s59
	global_load_lds_dwordx4 v[222:223], off
	v_lshl_add_u64 v[224:225], s[40:41], 0, v[0:1]
	s_mov_b32 m0, s27
	v_lshl_add_u64 v[226:227], s[36:37], 0, v[152:153]
	global_load_lds_dwordx4 v[224:225], off
	v_lshl_add_u64 v[224:225], s[40:41], 0, v[154:155]
	s_add_i32 m0, s27, 0x2000
	s_nop 0
	global_load_lds_dwordx4 v[224:225], off
	v_lshl_add_u64 v[224:225], s[36:37], 0, v[150:151]
	s_mov_b32 m0, s29
	s_nop 0
	global_load_lds_dwordx4 v[224:225], off
	s_mov_b32 m0, s52
	s_nop 0
	global_load_lds_dwordx4 v[226:227], off
	s_waitcnt vmcnt(8)
	s_waitcnt lgkmcnt(0)
	s_barrier
; #define PG8_STAGE(bufoff, gbase, voff) do { _Pragma("unroll") for (int _i = 0; _i < 2; ++_i) \
;         __builtin_amdgcn_global_load_lds((const unsigned*)((const char*)(gbase) + (voff)[_i]), (PG8_LAS unsigned*)(lds + (bufoff) + ldsw + _i * 8192), 16, 0, 0); } while (0)
; #define PG8_LDA(dst, b, h) do { _Pragma("unroll") for (int m = 0; m < 4; ++m) _Pragma("unroll") for (int k = 0; k < 2; ++k) dst[m][k] = *(const PG8_LAS bf16x8*)(lds + PG8_SA(b, h) + aoff + m * 2048 + k * 1024); } while (0)
; #define PG8_LDB(dst, b, h) do { _Pragma("unroll") for (int n = 0; n < 2; ++n) _Pragma("unroll") for (int k = 0; k < 2; ++k) dst[n][k] = *(const PG8_LAS bf16x8*)(lds + PG8_SB(b, h) + boff + n * 2048 + k * 1024); } while (0)
; #define PG8_MMA(ai, bj, At, Bt) do { __builtin_amdgcn_s_setprio(1); _Pragma("unroll") for (int m = 0; m < 4; ++m) _Pragma("unroll") for (int n = 0; n < 2; ++n) _Pragma("unroll") for (int k = 0; k < 2; ++k) \
;         acc[ai][bj][m][n] = __builtin_amdgcn_mfma_f32_16x16x32_bf16(Bt[n][k], At[m][k], acc[ai][bj][m][n], 0, 0, 0); __builtin_amdgcn_s_setprio(0); } while (0)
; #define PG8_WAIT_V(n) asm volatile("s_waitcnt vmcnt(" #n ")" ::: "memory")
; #define PG8_WAIT_L(n) asm volatile("s_waitcnt lgkmcnt(" #n ")" ::: "memory")
; #define PG8_BAR __builtin_amdgcn_s_barrier()
; #define PG8_SCHED __builtin_amdgcn_sched_barrier(0)
; template <class Epi, class Sched, bool ALIGN_EPI = false, bool SP2 = false>
; __device__ __forceinline__ void gemm_phase(PG8_LAS unsigned char* lds, const Gemm g, const Sched& S, const Epi& E, int wid_in) {
;     ...
;             PG8_WAIT_V(8); PG8_WAIT_L(0); PG8_BAR; PG8_MMA(1, 0, At, B0); PG8_MMA(1, 1, At, B1); PG8_BAR; PG8_SCHED;
;             PG8_LDB(B0, 1, 0); PG8_LDB(B1, 1, 1); PG8_SCHED; PG8_LDA(At, 1, 0); PG8_STAGE(PG8_SA(0, 1), a2 + hstep, voffA);
;             PG8_WAIT_V(8); PG8_WAIT_L(0); PG8_BAR; PG8_MMA(0, 0, At, B0); PG8_MMA(0, 1, At, B1); PG8_BAR; PG8_SCHED;
	s_waitcnt lgkmcnt(0)
	v_mfma_f32_16x16x32_bf16 v[62:65], v[130:133], v[172:175], v[62:65]
	v_mfma_f32_16x16x32_bf16 v[58:61], v[138:141], v[172:175], v[58:61]
	v_mfma_f32_16x16x32_bf16 v[54:57], v[130:133], v[182:185], v[54:57]
	v_mfma_f32_16x16x32_bf16 v[50:53], v[138:141], v[182:185], v[50:53]
	v_mfma_f32_16x16x32_bf16 v[38:41], v[130:133], v[190:193], v[38:41]
	v_mfma_f32_16x16x32_bf16 v[34:37], v[138:141], v[190:193], v[34:37]
	v_mfma_f32_16x16x32_bf16 v[22:25], v[130:133], v[212:215], v[22:25]
	v_mfma_f32_16x16x32_bf16 v[18:21], v[138:141], v[212:215], v[18:21]
	v_mfma_f32_16x16x32_bf16 v[62:65], v[134:137], v[178:181], v[62:65]
	v_mfma_f32_16x16x32_bf16 v[58:61], v[142:145], v[178:181], v[58:61]
	v_mfma_f32_16x16x32_bf16 v[54:57], v[134:137], v[186:189], v[54:57]
	v_mfma_f32_16x16x32_bf16 v[50:53], v[142:145], v[186:189], v[50:53]
	v_mfma_f32_16x16x32_bf16 v[38:41], v[134:137], v[208:211], v[38:41]
	v_mfma_f32_16x16x32_bf16 v[34:37], v[142:145], v[208:211], v[34:37]
	v_mfma_f32_16x16x32_bf16 v[22:25], v[134:137], v[216:219], v[22:25]
	v_mfma_f32_16x16x32_bf16 v[18:21], v[142:145], v[216:219], v[18:21]
	v_mfma_f32_16x16x32_bf16 v[46:49], v[146:149], v[172:175], v[46:49]
	v_mfma_f32_16x16x32_bf16 v[42:45], v[164:167], v[172:175], v[42:45]
	v_mfma_f32_16x16x32_bf16 v[30:33], v[146:149], v[182:185], v[30:33]
	v_mfma_f32_16x16x32_bf16 v[26:29], v[164:167], v[182:185], v[26:29]
	v_mfma_f32_16x16x32_bf16 v[14:17], v[146:149], v[190:193], v[14:17]
	v_mfma_f32_16x16x32_bf16 v[10:13], v[164:167], v[190:193], v[10:13]
	v_mfma_f32_16x16x32_bf16 v[6:9], v[146:149], v[212:215], v[6:9]
	v_mfma_f32_16x16x32_bf16 v[2:5], v[164:167], v[212:215], v[2:5]
	v_mfma_f32_16x16x32_bf16 v[46:49], v[160:163], v[178:181], v[46:49]
	v_mfma_f32_16x16x32_bf16 v[42:45], v[168:171], v[178:181], v[42:45]
	v_mfma_f32_16x16x32_bf16 v[30:33], v[160:163], v[186:189], v[30:33]
	v_mfma_f32_16x16x32_bf16 v[26:29], v[168:171], v[186:189], v[26:29]
	v_mfma_f32_16x16x32_bf16 v[14:17], v[160:163], v[208:211], v[14:17]
	v_mfma_f32_16x16x32_bf16 v[10:13], v[168:171], v[208:211], v[10:13]
	v_mfma_f32_16x16x32_bf16 v[6:9], v[160:163], v[216:219], v[6:9]
	v_mfma_f32_16x16x32_bf16 v[2:5], v[168:171], v[216:219], v[2:5]
	s_barrier
	s_add_i32 s27, 0, 0x18000
	s_add_i32 s40, 0, 0x1c000
	v_add_u32_e32 v142, s27, v176
	v_add_u32_e32 v168, s40, v176
	ds_read_b128 v[130:133], v142
	ds_read_b128 v[134:137], v142 offset:1024
	ds_read_b128 v[138:141], v142 offset:2048
	ds_read_b128 v[142:145], v142 offset:3072
	ds_read_b128 v[146:149], v168
	ds_read_b128 v[160:163], v168 offset:1024
	ds_read_b128 v[164:167], v168 offset:2048
	ds_read_b128 v[168:171], v168 offset:3072
	s_add_u32 s36, s36, 0x80000
	s_addc_u32 s37, s37, 0
	s_mov_b32 m0, s53
	v_lshl_add_u64 v[228:229], s[36:37], 0, v[150:151]
	ds_read_b128 v[172:175], v177 offset:32768
	ds_read_b128 v[178:181], v177 offset:33792
	ds_read_b128 v[182:185], v177 offset:34816
	ds_read_b128 v[186:189], v177 offset:35840
	ds_read_b128 v[190:193], v177 offset:36864
	ds_read_b128 v[208:211], v177 offset:37888
	ds_read_b128 v[212:215], v177 offset:38912
	ds_read_b128 v[216:219], v177 offset:39936
	global_load_lds_dwordx4 v[228:229], off
	v_lshl_add_u64 v[228:229], s[36:37], 0, v[152:153]
	s_mov_b32 m0, s61
	s_nop 0
	global_load_lds_dwordx4 v[228:229], off
	s_waitcnt vmcnt(8)
	s_waitcnt lgkmcnt(0)
	s_barrier
	s_waitcnt lgkmcnt(0)
	v_mfma_f32_16x16x32_bf16 v[126:129], v[130:133], v[172:175], v[126:129]
	v_mfma_f32_16x16x32_bf16 v[122:125], v[138:141], v[172:175], v[122:125]
	v_mfma_f32_16x16x32_bf16 v[118:121], v[130:133], v[182:185], v[118:121]
	v_mfma_f32_16x16x32_bf16 v[114:117], v[138:141], v[182:185], v[114:117]
	v_mfma_f32_16x16x32_bf16 v[102:105], v[130:133], v[190:193], v[102:105]
	v_mfma_f32_16x16x32_bf16 v[98:101], v[138:141], v[190:193], v[98:101]
	v_mfma_f32_16x16x32_bf16 v[86:89], v[130:133], v[212:215], v[86:89]
	v_mfma_f32_16x16x32_bf16 v[82:85], v[138:141], v[212:215], v[82:85]
	v_mfma_f32_16x16x32_bf16 v[126:129], v[134:137], v[178:181], v[126:129]
	v_mfma_f32_16x16x32_bf16 v[122:125], v[142:145], v[178:181], v[122:125]
	v_mfma_f32_16x16x32_bf16 v[118:121], v[134:137], v[186:189], v[118:121]
	v_mfma_f32_16x16x32_bf16 v[114:117], v[142:145], v[186:189], v[114:117]
	v_mfma_f32_16x16x32_bf16 v[102:105], v[134:137], v[208:211], v[102:105]
	v_mfma_f32_16x16x32_bf16 v[98:101], v[142:145], v[208:211], v[98:101]
	v_mfma_f32_16x16x32_bf16 v[86:89], v[134:137], v[216:219], v[86:89]
	v_mfma_f32_16x16x32_bf16 v[82:85], v[142:145], v[216:219], v[82:85]
	v_mfma_f32_16x16x32_bf16 v[110:113], v[146:149], v[172:175], v[110:113]
	v_mfma_f32_16x16x32_bf16 v[106:109], v[164:167], v[172:175], v[106:109]
	v_mfma_f32_16x16x32_bf16 v[94:97], v[146:149], v[182:185], v[94:97]
	v_mfma_f32_16x16x32_bf16 v[90:93], v[164:167], v[182:185], v[90:93]
	v_mfma_f32_16x16x32_bf16 v[78:81], v[146:149], v[190:193], v[78:81]
	v_mfma_f32_16x16x32_bf16 v[74:77], v[164:167], v[190:193], v[74:77]
	v_mfma_f32_16x16x32_bf16 v[70:73], v[146:149], v[212:215], v[70:73]
	v_mfma_f32_16x16x32_bf16 v[66:69], v[164:167], v[212:215], v[66:69]
	v_mfma_f32_16x16x32_bf16 v[110:113], v[160:163], v[178:181], v[110:113]
	v_mfma_f32_16x16x32_bf16 v[106:109], v[168:171], v[178:181], v[106:109]
	v_mfma_f32_16x16x32_bf16 v[94:97], v[160:163], v[186:189], v[94:97]
	v_mfma_f32_16x16x32_bf16 v[90:93], v[168:171], v[186:189], v[90:93]
	v_mfma_f32_16x16x32_bf16 v[78:81], v[160:163], v[208:211], v[78:81]
	v_mfma_f32_16x16x32_bf16 v[74:77], v[168:171], v[208:211], v[74:77]
	v_mfma_f32_16x16x32_bf16 v[70:73], v[160:163], v[216:219], v[70:73]
	v_mfma_f32_16x16x32_bf16 v[66:69], v[168:171], v[216:219], v[66:69]
	s_barrier
; #define PG8_STAGE(bufoff, gbase, voff) do { _Pragma("unroll") for (int _i = 0; _i < 2; ++_i) \
;         __builtin_amdgcn_global_load_lds((const unsigned*)((const char*)(gbase) + (voff)[_i]), (PG8_LAS unsigned*)(lds + (bufoff) + ldsw + _i * 8192), 16, 0, 0); } while (0)
; #define PG8_LDA(dst, b, h) do { _Pragma("unroll") for (int m = 0; m < 4; ++m) _Pragma("unroll") for (int k = 0; k < 2; ++k) dst[m][k] = *(const PG8_LAS bf16x8*)(lds + PG8_SA(b, h) + aoff + m * 2048 + k * 1024); } while (0)
; #define PG8_MMA(ai, bj, At, Bt) do { __builtin_amdgcn_s_setprio(1); _Pragma("unroll") for (int m = 0; m < 4; ++m) _Pragma("unroll") for (int n = 0; n < 2; ++n) _Pragma("unroll") for (int k = 0; k < 2; ++k) \
;         acc[ai][bj][m][n] = __builtin_amdgcn_mfma_f32_16x16x32_bf16(Bt[n][k], At[m][k], acc[ai][bj][m][n], 0, 0, 0); __builtin_amdgcn_s_setprio(0); } while (0)
; #define PG8_WAIT_V(n) asm volatile("s_waitcnt vmcnt(" #n ")" ::: "memory")
; #define PG8_WAIT_L(n) asm volatile("s_waitcnt lgkmcnt(" #n ")" ::: "memory")
; #define PG8_BAR __builtin_amdgcn_s_barrier()
; #define PG8_SCHED __builtin_amdgcn_sched_barrier(0)
; template <class Epi, class Sched, bool ALIGN_EPI = false, bool SP2 = false>
; __device__ __forceinline__ void gemm_phase(PG8_LAS unsigned char* lds, const Gemm g, const Sched& S, const Epi& E, int wid_in) {
;     ...
;         for (int t = 0; t < nt; t += 2) {
;             const bool last = (t == nt - 2);
;             const char* a1 = cA + (size_t)(t + 1) * kstep;
;             const char* a2 = last ? nA : cA + (size_t)(t + 2) * kstep; const char* b2 = last ? nB : cB + (size_t)(t + 2) * kstep;
;     ...
;             PG8_LDA(At, 1, 1); PG8_STAGE(PG8_SB(1, 0), b3, voffB); PG8_STAGE(PG8_SB(1, 1), b3 + hstep, voffB); PG8_STAGE(PG8_SA(1, 0), a3, voffA);
;             PG8_WAIT_V(8); PG8_WAIT_L(0); PG8_BAR; PG8_MMA(1, 0, At, B0); PG8_MMA(1, 1, At, B1); PG8_BAR; PG8_SCHED;
	s_add_i32 s27, s27, s59
	v_lshl_add_u64 v[220:221], v[220:221], 0, s[94:95]
	s_mov_b32 m0, s27
	ds_read_b128 v[172:175], v177 offset:49152
	ds_read_b128 v[178:181], v177 offset:50176
	ds_read_b128 v[182:185], v177 offset:51200
	ds_read_b128 v[186:189], v177 offset:52224
	ds_read_b128 v[190:193], v177 offset:53248
	ds_read_b128 v[208:211], v177 offset:54272
	ds_read_b128 v[212:215], v177 offset:55296
	ds_read_b128 v[216:219], v177 offset:56320
	global_load_lds_dwordx4 v[220:221], off
	s_add_i32 m0, s27, 0x2000
	s_add_u32 s34, s34, 0x80080
	v_lshl_add_u64 v[220:221], v[222:223], 0, s[94:95]
	s_addc_u32 s35, s35, 0
	s_add_i32 s27, s40, s59
	global_load_lds_dwordx4 v[220:221], off
	v_lshl_add_u64 v[220:221], s[34:35], 0, v[0:1]
	s_mov_b32 m0, s27
	s_nop 0
	global_load_lds_dwordx4 v[220:221], off
	v_lshl_add_u64 v[220:221], s[34:35], 0, v[154:155]
	s_add_i32 m0, s27, 0x2000
	s_nop 0
	global_load_lds_dwordx4 v[220:221], off
	v_lshl_add_u64 v[220:221], v[224:225], 0, s[94:95]
	s_mov_b32 m0, s73
	s_nop 0
	global_load_lds_dwordx4 v[220:221], off
	v_lshl_add_u64 v[220:221], v[226:227], 0, s[94:95]
	s_mov_b32 m0, s80
	s_nop 0
	global_load_lds_dwordx4 v[220:221], off
	s_waitcnt vmcnt(8)
	s_waitcnt lgkmcnt(0)
	s_barrier
	s_waitcnt lgkmcnt(0)
	v_mfma_f32_16x16x32_bf16 v[62:65], v[130:133], v[172:175], v[62:65]
	v_mfma_f32_16x16x32_bf16 v[58:61], v[138:141], v[172:175], v[58:61]
	v_mfma_f32_16x16x32_bf16 v[54:57], v[130:133], v[182:185], v[54:57]
	v_mfma_f32_16x16x32_bf16 v[50:53], v[138:141], v[182:185], v[50:53]
	v_mfma_f32_16x16x32_bf16 v[38:41], v[130:133], v[190:193], v[38:41]
	v_mfma_f32_16x16x32_bf16 v[34:37], v[138:141], v[190:193], v[34:37]
	v_mfma_f32_16x16x32_bf16 v[22:25], v[130:133], v[212:215], v[22:25]
	v_mfma_f32_16x16x32_bf16 v[18:21], v[138:141], v[212:215], v[18:21]
	v_mfma_f32_16x16x32_bf16 v[62:65], v[134:137], v[178:181], v[62:65]
	v_mfma_f32_16x16x32_bf16 v[58:61], v[142:145], v[178:181], v[58:61]
	v_mfma_f32_16x16x32_bf16 v[54:57], v[134:137], v[186:189], v[54:57]
	v_mfma_f32_16x16x32_bf16 v[50:53], v[142:145], v[186:189], v[50:53]
	v_mfma_f32_16x16x32_bf16 v[38:41], v[134:137], v[208:211], v[38:41]
	v_mfma_f32_16x16x32_bf16 v[34:37], v[142:145], v[208:211], v[34:37]
	v_mfma_f32_16x16x32_bf16 v[22:25], v[134:137], v[216:219], v[22:25]
	v_mfma_f32_16x16x32_bf16 v[18:21], v[142:145], v[216:219], v[18:21]
	v_mfma_f32_16x16x32_bf16 v[46:49], v[146:149], v[172:175], v[46:49]
	v_mfma_f32_16x16x32_bf16 v[42:45], v[164:167], v[172:175], v[42:45]
	v_mfma_f32_16x16x32_bf16 v[30:33], v[146:149], v[182:185], v[30:33]
	v_mfma_f32_16x16x32_bf16 v[26:29], v[164:167], v[182:185], v[26:29]
	v_mfma_f32_16x16x32_bf16 v[14:17], v[146:149], v[190:193], v[14:17]
	v_mfma_f32_16x16x32_bf16 v[10:13], v[164:167], v[190:193], v[10:13]
	v_mfma_f32_16x16x32_bf16 v[6:9], v[146:149], v[212:215], v[6:9]
	v_mfma_f32_16x16x32_bf16 v[2:5], v[164:167], v[212:215], v[2:5]
	v_mfma_f32_16x16x32_bf16 v[46:49], v[160:163], v[178:181], v[46:49]
	v_mfma_f32_16x16x32_bf16 v[42:45], v[168:171], v[178:181], v[42:45]
	v_mfma_f32_16x16x32_bf16 v[30:33], v[160:163], v[186:189], v[30:33]
	v_mfma_f32_16x16x32_bf16 v[26:29], v[168:171], v[186:189], v[26:29]
	v_mfma_f32_16x16x32_bf16 v[14:17], v[160:163], v[208:211], v[14:17]
	v_mfma_f32_16x16x32_bf16 v[10:13], v[168:171], v[208:211], v[10:13]
	v_mfma_f32_16x16x32_bf16 v[6:9], v[160:163], v[216:219], v[6:9]
	v_mfma_f32_16x16x32_bf16 v[2:5], v[168:171], v[216:219], v[2:5]
	s_barrier
	s_add_u32 s19, s19, 0x100
	s_addc_u32 s21, s21, 0
	s_add_u32 s30, s30, 0x100
	s_addc_u32 s31, s31, 0
	s_cmp_ge_i32 s56, s90
	s_mov_b32 s27, s56
	s_cbranch_scc0 .LBB0_1021
	s_and_b64 vcc, exec, s[14:15]
	s_cbranch_vccz .LBB0_1024
	s_barrier

; #define PG8_STAGE(bufoff, gbase, voff) do { _Pragma("unroll") for (int _i = 0; _i < 2; ++_i) \
;         __builtin_amdgcn_global_load_lds((const unsigned*)((const char*)(gbase) + (voff)[_i]), (PG8_LAS unsigned*)(lds + (bufoff) + ldsw + _i * 8192), 16, 0, 0); } while (0)
; #define PG8_LDA(dst, b, h) do { _Pragma("unroll") for (int m = 0; m < 4; ++m) _Pragma("unroll") for (int k = 0; k < 2; ++k) dst[m][k] = *(const PG8_LAS bf16x8*)(lds + PG8_SA(b, h) + aoff + m * 2048 + k * 1024); } while (0)
; #define PG8_LDB(dst, b, h) do { _Pragma("unroll") for (int n = 0; n < 2; ++n) _Pragma("unroll") for (int k = 0; k < 2; ++k) dst[n][k] = *(const PG8_LAS bf16x8*)(lds + PG8_SB(b, h) + boff + n * 2048 + k * 1024); } while (0)
; #define PG8_MMA(ai, bj, At, Bt) do { __builtin_amdgcn_s_setprio(1); _Pragma("unroll") for (int m = 0; m < 4; ++m) _Pragma("unroll") for (int n = 0; n < 2; ++n) _Pragma("unroll") for (int k = 0; k < 2; ++k) \
;         acc[ai][bj][m][n] = __builtin_amdgcn_mfma_f32_16x16x32_bf16(Bt[n][k], At[m][k], acc[ai][bj][m][n], 0, 0, 0); __builtin_amdgcn_s_setprio(0); } while (0)
; #define PG8_WAIT_V(n) asm volatile("s_waitcnt vmcnt(" #n ")" ::: "memory")
; #define PG8_BAR __builtin_amdgcn_s_barrier()
; template <class Epi, class Sched, bool ALIGN_EPI = false, bool SP2 = false>
; __device__ __forceinline__ void gemm_phase(PG8_LAS unsigned char* lds, const Gemm g, const Sched& S, const Epi& E, int wid_in) {
;     ...
;         for (int t = 0; t < nt; t += 2) {
;             const bool last = (t == nt - 2);
;             const char* a1 = cA + (size_t)(t + 1) * kstep;
;             const char* a2 = last ? nA : cA + (size_t)(t + 2) * kstep; const char* b2 = last ? nB : cB + (size_t)(t + 2) * kstep;
;             const char* a3 = a2 + kstep; const char* b3 = b2 + kstep;
;             if (last && has_next) S.a_ready(nxt);
;             if constexpr (SP2) {
;             PG8_LDB(B0, 0, 0); PG8_LDB(B1, 0, 1); PG8_SCHED; PG8_LDA(At, 0, 0); PG8_STAGE(PG8_SA(1, 1), a1 + hstep, voffA);
;             PG8_WAIT_V(8); PG8_WAIT_L(0); PG8_BAR; PG8_MMA(0, 0, At, B0); PG8_MMA(0, 1, At, B1); PG8_BAR; PG8_SCHED;
;             PG8_LDA(At, 0, 1); PG8_STAGE(PG8_SB(0, 0), b2, voffB); PG8_STAGE(PG8_SB(0, 1), b2 + hstep, voffB); PG8_STAGE(PG8_SA(0, 0), a2, voffA);
;             PG8_WAIT_V(8); PG8_WAIT_L(0); PG8_BAR; PG8_MMA(1, 0, At, B0); PG8_MMA(1, 1, At, B1); PG8_BAR; PG8_SCHED;
.LBB0_1153:
	s_add_u32 s26, s24, 0xfff80080
	s_addc_u32 s27, s25, -1
	s_add_i32 s40, 0, 0x10000
	s_cmp_eq_u32 s73, 28
	s_cselect_b32 s29, s19, s27
	s_cselect_b32 s28, s64, s26
	v_add_u32_e32 v140, s40, v142
	s_cselect_b32 s27, s17, s63
	s_cselect_b32 s26, s65, s72
	s_add_i32 s42, 0, 0x14000
	ds_read_b128 v[144:147], v140
	ds_read_b128 v[148:151], v140 offset:1024
	ds_read_b128 v[152:155], v140 offset:2048
	ds_read_b128 v[156:159], v140 offset:3072
	v_add_u32_e32 v140, s42, v142
	ds_read_b128 v[160:163], v140
	ds_read_b128 v[164:167], v140 offset:1024
	ds_read_b128 v[168:171], v140 offset:2048
	ds_read_b128 v[172:175], v140 offset:3072
	v_lshl_add_u64 v[140:141], s[24:25], 0, v[138:139]
	s_add_i32 m0, s34, 0xc000
	ds_read_b128 v[176:179], v143
	ds_read_b128 v[180:183], v143 offset:1024
	ds_read_b128 v[184:187], v143 offset:2048
	ds_read_b128 v[188:191], v143 offset:3072
	ds_read_b128 v[208:211], v143 offset:4096
	ds_read_b128 v[212:215], v143 offset:5120
	ds_read_b128 v[216:219], v143 offset:6144
	ds_read_b128 v[220:223], v143 offset:7168
	global_load_lds_dwordx4 v[140:141], off
	v_lshl_add_u64 v[140:141], s[24:25], 0, v[136:137]
	s_add_i32 m0, s34, 0xe000
	s_nop 0
	global_load_lds_dwordx4 v[140:141], off
	s_waitcnt vmcnt(8)
	s_waitcnt lgkmcnt(0)
	s_barrier
	s_waitcnt lgkmcnt(0)
	v_mfma_f32_16x16x32_bf16 v[126:129], v[144:147], v[176:179], v[126:129]
	v_mfma_f32_16x16x32_bf16 v[122:125], v[152:155], v[176:179], v[122:125]
	v_mfma_f32_16x16x32_bf16 v[110:113], v[144:147], v[184:187], v[110:113]
	v_mfma_f32_16x16x32_bf16 v[106:109], v[152:155], v[184:187], v[106:109]
	v_mfma_f32_16x16x32_bf16 v[94:97], v[144:147], v[208:211], v[94:97]
	v_mfma_f32_16x16x32_bf16 v[90:93], v[152:155], v[208:211], v[90:93]
	v_mfma_f32_16x16x32_bf16 v[78:81], v[144:147], v[216:219], v[78:81]
	v_mfma_f32_16x16x32_bf16 v[74:77], v[152:155], v[216:219], v[74:77]
	v_mfma_f32_16x16x32_bf16 v[126:129], v[148:151], v[180:183], v[126:129]
	v_mfma_f32_16x16x32_bf16 v[122:125], v[156:159], v[180:183], v[122:125]
	v_mfma_f32_16x16x32_bf16 v[110:113], v[148:151], v[188:191], v[110:113]
	v_mfma_f32_16x16x32_bf16 v[106:109], v[156:159], v[188:191], v[106:109]
	v_mfma_f32_16x16x32_bf16 v[94:97], v[148:151], v[212:215], v[94:97]
	v_mfma_f32_16x16x32_bf16 v[90:93], v[156:159], v[212:215], v[90:93]
	v_mfma_f32_16x16x32_bf16 v[78:81], v[148:151], v[220:223], v[78:81]
	v_mfma_f32_16x16x32_bf16 v[74:77], v[156:159], v[220:223], v[74:77]
	v_mfma_f32_16x16x32_bf16 v[118:121], v[160:163], v[176:179], v[118:121]
	v_mfma_f32_16x16x32_bf16 v[114:117], v[168:171], v[176:179], v[114:117]
	v_mfma_f32_16x16x32_bf16 v[102:105], v[160:163], v[184:187], v[102:105]
	v_mfma_f32_16x16x32_bf16 v[98:101], v[168:171], v[184:187], v[98:101]
	v_mfma_f32_16x16x32_bf16 v[86:89], v[160:163], v[208:211], v[86:89]
	v_mfma_f32_16x16x32_bf16 v[82:85], v[168:171], v[208:211], v[82:85]
	v_mfma_f32_16x16x32_bf16 v[70:73], v[160:163], v[216:219], v[70:73]
	v_mfma_f32_16x16x32_bf16 v[66:69], v[168:171], v[216:219], v[66:69]
	v_mfma_f32_16x16x32_bf16 v[118:121], v[164:167], v[180:183], v[118:121]
	v_mfma_f32_16x16x32_bf16 v[114:117], v[172:175], v[180:183], v[114:117]
	v_mfma_f32_16x16x32_bf16 v[102:105], v[164:167], v[188:191], v[102:105]
	v_mfma_f32_16x16x32_bf16 v[98:101], v[172:175], v[188:191], v[98:101]
	v_mfma_f32_16x16x32_bf16 v[86:89], v[164:167], v[212:215], v[86:89]
	v_mfma_f32_16x16x32_bf16 v[82:85], v[172:175], v[212:215], v[82:85]
	v_mfma_f32_16x16x32_bf16 v[70:73], v[164:167], v[220:223], v[70:73]
	v_mfma_f32_16x16x32_bf16 v[66:69], v[172:175], v[220:223], v[66:69]
	s_barrier
	s_add_i32 s40, s40, s59
	v_lshl_add_u64 v[140:141], s[26:27], 0, v[0:1]
	s_mov_b32 m0, s40
	ds_read_b128 v[176:179], v143 offset:16384
	ds_read_b128 v[180:183], v143 offset:17408
	ds_read_b128 v[184:187], v143 offset:18432
	ds_read_b128 v[188:191], v143 offset:19456
	ds_read_b128 v[208:211], v143 offset:20480
	ds_read_b128 v[212:215], v143 offset:21504
	ds_read_b128 v[216:219], v143 offset:22528
	ds_read_b128 v[220:223], v143 offset:23552
	global_load_lds_dwordx4 v[140:141], off
	s_add_i32 m0, s40, 0x2000
	s_add_u32 s40, s26, 0x80000
	v_lshl_add_u64 v[192:193], s[26:27], 0, v[130:131]
	s_addc_u32 s41, s27, 0
	s_add_i32 s42, s42, s59
	global_load_lds_dwordx4 v[192:193], off
	v_lshl_add_u64 v[224:225], s[40:41], 0, v[0:1]
	s_mov_b32 m0, s42
	v_lshl_add_u64 v[226:227], s[28:29], 0, v[132:133]
	global_load_lds_dwordx4 v[224:225], off
	v_lshl_add_u64 v[224:225], s[40:41], 0, v[130:131]
	s_add_i32 m0, s42, 0x2000
	s_nop 0
	global_load_lds_dwordx4 v[224:225], off
	v_lshl_add_u64 v[224:225], s[28:29], 0, v[134:135]
	s_mov_b32 m0, s34
	s_nop 0
	global_load_lds_dwordx4 v[224:225], off
	s_mov_b32 m0, s35
	s_nop 0
	global_load_lds_dwordx4 v[226:227], off
	s_waitcnt vmcnt(8)
	s_waitcnt lgkmcnt(0)
	s_barrier
; #define PG8_STAGE(bufoff, gbase, voff) do { _Pragma("unroll") for (int _i = 0; _i < 2; ++_i) \
;         __builtin_amdgcn_global_load_lds((const unsigned*)((const char*)(gbase) + (voff)[_i]), (PG8_LAS unsigned*)(lds + (bufoff) + ldsw + _i * 8192), 16, 0, 0); } while (0)
; #define PG8_LDA(dst, b, h) do { _Pragma("unroll") for (int m = 0; m < 4; ++m) _Pragma("unroll") for (int k = 0; k < 2; ++k) dst[m][k] = *(const PG8_LAS bf16x8*)(lds + PG8_SA(b, h) + aoff + m * 2048 + k * 1024); } while (0)
; #define PG8_LDB(dst, b, h) do { _Pragma("unroll") for (int n = 0; n < 2; ++n) _Pragma("unroll") for (int k = 0; k < 2; ++k) dst[n][k] = *(const PG8_LAS bf16x8*)(lds + PG8_SB(b, h) + boff + n * 2048 + k * 1024); } while (0)
; #define PG8_MMA(ai, bj, At, Bt) do { __builtin_amdgcn_s_setprio(1); _Pragma("unroll") for (int m = 0; m < 4; ++m) _Pragma("unroll") for (int n = 0; n < 2; ++n) _Pragma("unroll") for (int k = 0; k < 2; ++k) \
;         acc[ai][bj][m][n] = __builtin_amdgcn_mfma_f32_16x16x32_bf16(Bt[n][k], At[m][k], acc[ai][bj][m][n], 0, 0, 0); __builtin_amdgcn_s_setprio(0); } while (0)
; #define PG8_WAIT_V(n) asm volatile("s_waitcnt vmcnt(" #n ")" ::: "memory")
; #define PG8_WAIT_L(n) asm volatile("s_waitcnt lgkmcnt(" #n ")" ::: "memory")
; #define PG8_BAR __builtin_amdgcn_s_barrier()
; #define PG8_SCHED __builtin_amdgcn_sched_barrier(0)
; template <class Epi, class Sched, bool ALIGN_EPI = false, bool SP2 = false>
; __device__ __forceinline__ void gemm_phase(PG8_LAS unsigned char* lds, const Gemm g, const Sched& S, const Epi& E, int wid_in) {
;     ...
;             PG8_WAIT_V(8); PG8_WAIT_L(0); PG8_BAR; PG8_MMA(1, 0, At, B0); PG8_MMA(1, 1, At, B1); PG8_BAR; PG8_SCHED;
;             PG8_LDB(B0, 1, 0); PG8_LDB(B1, 1, 1); PG8_SCHED; PG8_LDA(At, 1, 0); PG8_STAGE(PG8_SA(0, 1), a2 + hstep, voffA);
;             PG8_WAIT_V(8); PG8_WAIT_L(0); PG8_BAR; PG8_MMA(0, 0, At, B0); PG8_MMA(0, 1, At, B1); PG8_BAR; PG8_SCHED;
	s_waitcnt lgkmcnt(0)
	v_mfma_f32_16x16x32_bf16 v[62:65], v[144:147], v[176:179], v[62:65]
	v_mfma_f32_16x16x32_bf16 v[58:61], v[152:155], v[176:179], v[58:61]
	v_mfma_f32_16x16x32_bf16 v[46:49], v[144:147], v[184:187], v[46:49]
	v_mfma_f32_16x16x32_bf16 v[42:45], v[152:155], v[184:187], v[42:45]
	v_mfma_f32_16x16x32_bf16 v[30:33], v[144:147], v[208:211], v[30:33]
	v_mfma_f32_16x16x32_bf16 v[26:29], v[152:155], v[208:211], v[26:29]
	v_mfma_f32_16x16x32_bf16 v[14:17], v[144:147], v[216:219], v[14:17]
	v_mfma_f32_16x16x32_bf16 v[10:13], v[152:155], v[216:219], v[10:13]
	v_mfma_f32_16x16x32_bf16 v[62:65], v[148:151], v[180:183], v[62:65]
	v_mfma_f32_16x16x32_bf16 v[58:61], v[156:159], v[180:183], v[58:61]
	v_mfma_f32_16x16x32_bf16 v[46:49], v[148:151], v[188:191], v[46:49]
	v_mfma_f32_16x16x32_bf16 v[42:45], v[156:159], v[188:191], v[42:45]
	v_mfma_f32_16x16x32_bf16 v[30:33], v[148:151], v[212:215], v[30:33]
	v_mfma_f32_16x16x32_bf16 v[26:29], v[156:159], v[212:215], v[26:29]
	v_mfma_f32_16x16x32_bf16 v[14:17], v[148:151], v[220:223], v[14:17]
	v_mfma_f32_16x16x32_bf16 v[10:13], v[156:159], v[220:223], v[10:13]
	v_mfma_f32_16x16x32_bf16 v[54:57], v[160:163], v[176:179], v[54:57]
	v_mfma_f32_16x16x32_bf16 v[50:53], v[168:171], v[176:179], v[50:53]
	v_mfma_f32_16x16x32_bf16 v[38:41], v[160:163], v[184:187], v[38:41]
	v_mfma_f32_16x16x32_bf16 v[34:37], v[168:171], v[184:187], v[34:37]
	v_mfma_f32_16x16x32_bf16 v[22:25], v[160:163], v[208:211], v[22:25]
	v_mfma_f32_16x16x32_bf16 v[18:21], v[168:171], v[208:211], v[18:21]
	v_mfma_f32_16x16x32_bf16 v[6:9], v[160:163], v[216:219], v[6:9]
	v_mfma_f32_16x16x32_bf16 v[2:5], v[168:171], v[216:219], v[2:5]
	v_mfma_f32_16x16x32_bf16 v[54:57], v[164:167], v[180:183], v[54:57]
	v_mfma_f32_16x16x32_bf16 v[50:53], v[172:175], v[180:183], v[50:53]
	v_mfma_f32_16x16x32_bf16 v[38:41], v[164:167], v[188:191], v[38:41]
	v_mfma_f32_16x16x32_bf16 v[34:37], v[172:175], v[188:191], v[34:37]
	v_mfma_f32_16x16x32_bf16 v[22:25], v[164:167], v[212:215], v[22:25]
	v_mfma_f32_16x16x32_bf16 v[18:21], v[172:175], v[212:215], v[18:21]
	v_mfma_f32_16x16x32_bf16 v[6:9], v[164:167], v[220:223], v[6:9]
	v_mfma_f32_16x16x32_bf16 v[2:5], v[172:175], v[220:223], v[2:5]
	s_barrier
	s_add_i32 s40, 0, 0x18000
	s_add_i32 s41, 0, 0x1c000
	v_add_u32_e32 v156, s40, v142
	v_add_u32_e32 v172, s41, v142
	ds_read_b128 v[144:147], v156
	ds_read_b128 v[148:151], v156 offset:1024
	ds_read_b128 v[152:155], v156 offset:2048
	ds_read_b128 v[156:159], v156 offset:3072
	ds_read_b128 v[160:163], v172
	ds_read_b128 v[164:167], v172 offset:1024
	ds_read_b128 v[168:171], v172 offset:2048
	ds_read_b128 v[172:175], v172 offset:3072
	s_add_u32 s28, s28, 0x80000
	s_addc_u32 s29, s29, 0
	s_mov_b32 m0, s36
	v_lshl_add_u64 v[228:229], s[28:29], 0, v[134:135]
	ds_read_b128 v[176:179], v143 offset:32768
	ds_read_b128 v[180:183], v143 offset:33792
	ds_read_b128 v[184:187], v143 offset:34816
	ds_read_b128 v[188:191], v143 offset:35840
	ds_read_b128 v[208:211], v143 offset:36864
	ds_read_b128 v[212:215], v143 offset:37888
	ds_read_b128 v[216:219], v143 offset:38912
	ds_read_b128 v[220:223], v143 offset:39936
	global_load_lds_dwordx4 v[228:229], off
	v_lshl_add_u64 v[228:229], s[28:29], 0, v[132:133]
	s_mov_b32 m0, s37
	s_nop 0
	global_load_lds_dwordx4 v[228:229], off
	s_waitcnt vmcnt(8)
	s_waitcnt lgkmcnt(0)
	s_barrier
	s_waitcnt lgkmcnt(0)
	v_mfma_f32_16x16x32_bf16 v[126:129], v[144:147], v[176:179], v[126:129]
	v_mfma_f32_16x16x32_bf16 v[122:125], v[152:155], v[176:179], v[122:125]
	v_mfma_f32_16x16x32_bf16 v[110:113], v[144:147], v[184:187], v[110:113]
	v_mfma_f32_16x16x32_bf16 v[106:109], v[152:155], v[184:187], v[106:109]
	v_mfma_f32_16x16x32_bf16 v[94:97], v[144:147], v[208:211], v[94:97]
	v_mfma_f32_16x16x32_bf16 v[90:93], v[152:155], v[208:211], v[90:93]
	v_mfma_f32_16x16x32_bf16 v[78:81], v[144:147], v[216:219], v[78:81]
	v_mfma_f32_16x16x32_bf16 v[74:77], v[152:155], v[216:219], v[74:77]
	v_mfma_f32_16x16x32_bf16 v[126:129], v[148:151], v[180:183], v[126:129]
	v_mfma_f32_16x16x32_bf16 v[122:125], v[156:159], v[180:183], v[122:125]
	v_mfma_f32_16x16x32_bf16 v[110:113], v[148:151], v[188:191], v[110:113]
	v_mfma_f32_16x16x32_bf16 v[106:109], v[156:159], v[188:191], v[106:109]
	v_mfma_f32_16x16x32_bf16 v[94:97], v[148:151], v[212:215], v[94:97]
	v_mfma_f32_16x16x32_bf16 v[90:93], v[156:159], v[212:215], v[90:93]
	v_mfma_f32_16x16x32_bf16 v[78:81], v[148:151], v[220:223], v[78:81]
	v_mfma_f32_16x16x32_bf16 v[74:77], v[156:159], v[220:223], v[74:77]
	v_mfma_f32_16x16x32_bf16 v[118:121], v[160:163], v[176:179], v[118:121]
	v_mfma_f32_16x16x32_bf16 v[114:117], v[168:171], v[176:179], v[114:117]
	v_mfma_f32_16x16x32_bf16 v[102:105], v[160:163], v[184:187], v[102:105]
	v_mfma_f32_16x16x32_bf16 v[98:101], v[168:171], v[184:187], v[98:101]
	v_mfma_f32_16x16x32_bf16 v[86:89], v[160:163], v[208:211], v[86:89]
	v_mfma_f32_16x16x32_bf16 v[82:85], v[168:171], v[208:211], v[82:85]
	v_mfma_f32_16x16x32_bf16 v[70:73], v[160:163], v[216:219], v[70:73]
	v_mfma_f32_16x16x32_bf16 v[66:69], v[168:171], v[216:219], v[66:69]
	v_mfma_f32_16x16x32_bf16 v[118:121], v[164:167], v[180:183], v[118:121]
	v_mfma_f32_16x16x32_bf16 v[114:117], v[172:175], v[180:183], v[114:117]
	v_mfma_f32_16x16x32_bf16 v[102:105], v[164:167], v[188:191], v[102:105]
	v_mfma_f32_16x16x32_bf16 v[98:101], v[172:175], v[188:191], v[98:101]
	v_mfma_f32_16x16x32_bf16 v[86:89], v[164:167], v[212:215], v[86:89]
	v_mfma_f32_16x16x32_bf16 v[82:85], v[172:175], v[212:215], v[82:85]
	v_mfma_f32_16x16x32_bf16 v[70:73], v[164:167], v[220:223], v[70:73]
	v_mfma_f32_16x16x32_bf16 v[66:69], v[172:175], v[220:223], v[66:69]
	s_barrier
; #define PG8_STAGE(bufoff, gbase, voff) do { _Pragma("unroll") for (int _i = 0; _i < 2; ++_i) \
;         __builtin_amdgcn_global_load_lds((const unsigned*)((const char*)(gbase) + (voff)[_i]), (PG8_LAS unsigned*)(lds + (bufoff) + ldsw + _i * 8192), 16, 0, 0); } while (0)
; #define PG8_LDA(dst, b, h) do { _Pragma("unroll") for (int m = 0; m < 4; ++m) _Pragma("unroll") for (int k = 0; k < 2; ++k) dst[m][k] = *(const PG8_LAS bf16x8*)(lds + PG8_SA(b, h) + aoff + m * 2048 + k * 1024); } while (0)
; #define PG8_MMA(ai, bj, At, Bt) do { __builtin_amdgcn_s_setprio(1); _Pragma("unroll") for (int m = 0; m < 4; ++m) _Pragma("unroll") for (int n = 0; n < 2; ++n) _Pragma("unroll") for (int k = 0; k < 2; ++k) \
;         acc[ai][bj][m][n] = __builtin_amdgcn_mfma_f32_16x16x32_bf16(Bt[n][k], At[m][k], acc[ai][bj][m][n], 0, 0, 0); __builtin_amdgcn_s_setprio(0); } while (0)
; #define PG8_WAIT_V(n) asm volatile("s_waitcnt vmcnt(" #n ")" ::: "memory")
; #define PG8_WAIT_L(n) asm volatile("s_waitcnt lgkmcnt(" #n ")" ::: "memory")
; #define PG8_BAR __builtin_amdgcn_s_barrier()
; #define PG8_SCHED __builtin_amdgcn_sched_barrier(0)
; template <class Epi, class Sched, bool ALIGN_EPI = false, bool SP2 = false>
; __device__ __forceinline__ void gemm_phase(PG8_LAS unsigned char* lds, const Gemm g, const Sched& S, const Epi& E, int wid_in) {
;     ...
;         for (int t = 0; t < nt; t += 2) {
;             const bool last = (t == nt - 2);
;             const char* a1 = cA + (size_t)(t + 1) * kstep;
;             const char* a2 = last ? nA : cA + (size_t)(t + 2) * kstep; const char* b2 = last ? nB : cB + (size_t)(t + 2) * kstep;
;     ...
;             PG8_LDA(At, 1, 1); PG8_STAGE(PG8_SB(1, 0), b3, voffB); PG8_STAGE(PG8_SB(1, 1), b3 + hstep, voffB); PG8_STAGE(PG8_SA(1, 0), a3, voffA);
;             PG8_WAIT_V(8); PG8_WAIT_L(0); PG8_BAR; PG8_MMA(1, 0, At, B0); PG8_MMA(1, 1, At, B1); PG8_BAR; PG8_SCHED;
	s_add_i32 s28, s40, s59
	v_lshl_add_u64 v[140:141], v[140:141], 0, s[94:95]
	s_mov_b32 m0, s28
	ds_read_b128 v[176:179], v143 offset:49152
	ds_read_b128 v[180:183], v143 offset:50176
	ds_read_b128 v[184:187], v143 offset:51200
	ds_read_b128 v[188:191], v143 offset:52224
	ds_read_b128 v[208:211], v143 offset:53248
	ds_read_b128 v[212:215], v143 offset:54272
	ds_read_b128 v[216:219], v143 offset:55296
	ds_read_b128 v[220:223], v143 offset:56320
	global_load_lds_dwordx4 v[140:141], off
	s_add_i32 m0, s28, 0x2000
	s_add_u32 s26, s26, 0x80080
	v_lshl_add_u64 v[140:141], v[192:193], 0, s[94:95]
	s_addc_u32 s27, s27, 0
	s_add_i32 s28, s41, s59
	global_load_lds_dwordx4 v[140:141], off
	v_lshl_add_u64 v[140:141], s[26:27], 0, v[0:1]
	s_mov_b32 m0, s28
	s_nop 0
	global_load_lds_dwordx4 v[140:141], off
	v_lshl_add_u64 v[140:141], s[26:27], 0, v[130:131]
	s_add_i32 m0, s28, 0x2000
	s_nop 0
	global_load_lds_dwordx4 v[140:141], off
	v_lshl_add_u64 v[140:141], v[224:225], 0, s[94:95]
	s_mov_b32 m0, s48
	s_nop 0
	global_load_lds_dwordx4 v[140:141], off
	v_lshl_add_u64 v[140:141], v[226:227], 0, s[94:95]
	s_mov_b32 m0, s52
	s_nop 0
	global_load_lds_dwordx4 v[140:141], off
	s_waitcnt vmcnt(8)
	s_waitcnt lgkmcnt(0)
	s_barrier
	s_waitcnt lgkmcnt(0)
	v_mfma_f32_16x16x32_bf16 v[62:65], v[144:147], v[176:179], v[62:65]
	v_mfma_f32_16x16x32_bf16 v[58:61], v[152:155], v[176:179], v[58:61]
	v_mfma_f32_16x16x32_bf16 v[46:49], v[144:147], v[184:187], v[46:49]
	v_mfma_f32_16x16x32_bf16 v[42:45], v[152:155], v[184:187], v[42:45]
	v_mfma_f32_16x16x32_bf16 v[30:33], v[144:147], v[208:211], v[30:33]
	v_mfma_f32_16x16x32_bf16 v[26:29], v[152:155], v[208:211], v[26:29]
	v_mfma_f32_16x16x32_bf16 v[14:17], v[144:147], v[216:219], v[14:17]
	v_mfma_f32_16x16x32_bf16 v[10:13], v[152:155], v[216:219], v[10:13]
	v_mfma_f32_16x16x32_bf16 v[62:65], v[148:151], v[180:183], v[62:65]
	v_mfma_f32_16x16x32_bf16 v[58:61], v[156:159], v[180:183], v[58:61]
	v_mfma_f32_16x16x32_bf16 v[46:49], v[148:151], v[188:191], v[46:49]
	v_mfma_f32_16x16x32_bf16 v[42:45], v[156:159], v[188:191], v[42:45]
	v_mfma_f32_16x16x32_bf16 v[30:33], v[148:151], v[212:215], v[30:33]
	v_mfma_f32_16x16x32_bf16 v[26:29], v[156:159], v[212:215], v[26:29]
	v_mfma_f32_16x16x32_bf16 v[14:17], v[148:151], v[220:223], v[14:17]
	v_mfma_f32_16x16x32_bf16 v[10:13], v[156:159], v[220:223], v[10:13]
	v_mfma_f32_16x16x32_bf16 v[54:57], v[160:163], v[176:179], v[54:57]
	v_mfma_f32_16x16x32_bf16 v[50:53], v[168:171], v[176:179], v[50:53]
	v_mfma_f32_16x16x32_bf16 v[38:41], v[160:163], v[184:187], v[38:41]
	v_mfma_f32_16x16x32_bf16 v[34:37], v[168:171], v[184:187], v[34:37]
	v_mfma_f32_16x16x32_bf16 v[22:25], v[160:163], v[208:211], v[22:25]
	v_mfma_f32_16x16x32_bf16 v[18:21], v[168:171], v[208:211], v[18:21]
	v_mfma_f32_16x16x32_bf16 v[6:9], v[160:163], v[216:219], v[6:9]
	v_mfma_f32_16x16x32_bf16 v[2:5], v[168:171], v[216:219], v[2:5]
	v_mfma_f32_16x16x32_bf16 v[54:57], v[164:167], v[180:183], v[54:57]
	v_mfma_f32_16x16x32_bf16 v[50:53], v[172:175], v[180:183], v[50:53]
	v_mfma_f32_16x16x32_bf16 v[38:41], v[164:167], v[188:191], v[38:41]
	v_mfma_f32_16x16x32_bf16 v[34:37], v[172:175], v[188:191], v[34:37]
	v_mfma_f32_16x16x32_bf16 v[22:25], v[164:167], v[212:215], v[22:25]
	v_mfma_f32_16x16x32_bf16 v[18:21], v[172:175], v[212:215], v[18:21]
	v_mfma_f32_16x16x32_bf16 v[6:9], v[164:167], v[220:223], v[6:9]
	v_mfma_f32_16x16x32_bf16 v[2:5], v[172:175], v[220:223], v[2:5]
	s_barrier
	s_add_i32 s73, s73, 2
	s_add_u32 s72, s72, 0x100
	s_addc_u32 s63, s63, 0
	s_add_u32 s24, s24, 0x100
	s_addc_u32 s25, s25, 0
	s_cmp_gt_u32 s73, 29
	s_cbranch_scc0 .LBB0_1153
	s_and_b64 vcc, exec, s[14:15]
	s_cbranch_vccz .LBB0_1156
	s_barrier

; #define PG8_STAGE(bufoff, gbase, voff) do { _Pragma("unroll") for (int _i = 0; _i < 2; ++_i) \
;         __builtin_amdgcn_global_load_lds((const unsigned*)((const char*)(gbase) + (voff)[_i]), (PG8_LAS unsigned*)(lds + (bufoff) + ldsw + _i * 8192), 16, 0, 0); } while (0)
; #define PG8_LDA(dst, b, h) do { _Pragma("unroll") for (int m = 0; m < 4; ++m) _Pragma("unroll") for (int k = 0; k < 2; ++k) dst[m][k] = *(const PG8_LAS bf16x8*)(lds + PG8_SA(b, h) + aoff + m * 2048 + k * 1024); } while (0)
; #define PG8_LDB(dst, b, h) do { _Pragma("unroll") for (int n = 0; n < 2; ++n) _Pragma("unroll") for (int k = 0; k < 2; ++k) dst[n][k] = *(const PG8_LAS bf16x8*)(lds + PG8_SB(b, h) + boff + n * 2048 + k * 1024); } while (0)
; #define PG8_MMA(ai, bj, At, Bt) do { __builtin_amdgcn_s_setprio(1); _Pragma("unroll") for (int m = 0; m < 4; ++m) _Pragma("unroll") for (int n = 0; n < 2; ++n) _Pragma("unroll") for (int k = 0; k < 2; ++k) \
;         acc[ai][bj][m][n] = __builtin_amdgcn_mfma_f32_16x16x32_bf16(Bt[n][k], At[m][k], acc[ai][bj][m][n], 0, 0, 0); __builtin_amdgcn_s_setprio(0); } while (0)
; #define PG8_WAIT_V(n) asm volatile("s_waitcnt vmcnt(" #n ")" ::: "memory")
; #define PG8_BAR __builtin_amdgcn_s_barrier()
; template <class Epi, class Sched, bool ALIGN_EPI = false, bool SP2 = false>
; __device__ __forceinline__ void gemm_phase(PG8_LAS unsigned char* lds, const Gemm g, const Sched& S, const Epi& E, int wid_in) {
;     ...
;         for (int t = 0; t < nt; t += 2) {
;             const bool last = (t == nt - 2);
;             const char* a1 = cA + (size_t)(t + 1) * kstep;
;             const char* a2 = last ? nA : cA + (size_t)(t + 2) * kstep; const char* b2 = last ? nB : cB + (size_t)(t + 2) * kstep;
;             const char* a3 = a2 + kstep; const char* b3 = b2 + kstep;
;             if (last && has_next) S.a_ready(nxt);
;             if constexpr (SP2) {
;             PG8_LDB(B0, 0, 0); PG8_LDB(B1, 0, 1); PG8_SCHED; PG8_LDA(At, 0, 0); PG8_STAGE(PG8_SA(1, 1), a1 + hstep, voffA);
;             PG8_WAIT_V(8); PG8_WAIT_L(0); PG8_BAR; PG8_MMA(0, 0, At, B0); PG8_MMA(0, 1, At, B1); PG8_BAR; PG8_SCHED;
;             PG8_LDA(At, 0, 1); PG8_STAGE(PG8_SB(0, 0), b2, voffB); PG8_STAGE(PG8_SB(0, 1), b2 + hstep, voffB); PG8_STAGE(PG8_SA(0, 0), a2, voffA);
;             PG8_WAIT_V(8); PG8_WAIT_L(0); PG8_BAR; PG8_MMA(1, 0, At, B0); PG8_MMA(1, 1, At, B1); PG8_BAR; PG8_SCHED;
.LBB0_1233:
	s_add_i32 s56, s27, 2
	s_add_u32 s34, s30, 0xffe00080
	s_addc_u32 s35, s31, -1
	s_add_i32 s40, 0, 0x10000
	s_cmp_eq_u32 s17, s27
	s_cselect_b32 s37, s23, s35
	s_cselect_b32 s36, s22, s34
	s_cselect_b32 s35, s25, s21
	s_cselect_b32 s34, s24, s19
	s_add_i32 s27, 0, 0x14000
	v_add_u32_e32 v142, s40, v176
	v_add_u32_e32 v168, s27, v176
	ds_read_b128 v[130:133], v142
	ds_read_b128 v[134:137], v142 offset:1024
	ds_read_b128 v[138:141], v142 offset:2048
	ds_read_b128 v[142:145], v142 offset:3072
	ds_read_b128 v[146:149], v168
	ds_read_b128 v[160:163], v168 offset:1024
	ds_read_b128 v[164:167], v168 offset:2048
	ds_read_b128 v[168:171], v168 offset:3072
	v_lshl_add_u64 v[220:221], s[30:31], 0, v[158:159]
	s_add_i32 m0, s29, 0xc000
	ds_read_b128 v[172:175], v177
	ds_read_b128 v[178:181], v177 offset:1024
	ds_read_b128 v[182:185], v177 offset:2048
	ds_read_b128 v[186:189], v177 offset:3072
	ds_read_b128 v[190:193], v177 offset:4096
	ds_read_b128 v[208:211], v177 offset:5120
	ds_read_b128 v[212:215], v177 offset:6144
	ds_read_b128 v[216:219], v177 offset:7168
	global_load_lds_dwordx4 v[220:221], off
	v_lshl_add_u64 v[220:221], s[30:31], 0, v[156:157]
	s_add_i32 m0, s29, 0xe000
	s_nop 0
	global_load_lds_dwordx4 v[220:221], off
	s_waitcnt vmcnt(8)
	s_waitcnt lgkmcnt(0)
	s_barrier
	s_waitcnt lgkmcnt(0)
	v_mfma_f32_16x16x32_bf16 v[126:129], v[130:133], v[172:175], v[126:129]
	v_mfma_f32_16x16x32_bf16 v[122:125], v[138:141], v[172:175], v[122:125]
	v_mfma_f32_16x16x32_bf16 v[118:121], v[130:133], v[182:185], v[118:121]
	v_mfma_f32_16x16x32_bf16 v[114:117], v[138:141], v[182:185], v[114:117]
	v_mfma_f32_16x16x32_bf16 v[102:105], v[130:133], v[190:193], v[102:105]
	v_mfma_f32_16x16x32_bf16 v[98:101], v[138:141], v[190:193], v[98:101]
	v_mfma_f32_16x16x32_bf16 v[86:89], v[130:133], v[212:215], v[86:89]
	v_mfma_f32_16x16x32_bf16 v[82:85], v[138:141], v[212:215], v[82:85]
	v_mfma_f32_16x16x32_bf16 v[126:129], v[134:137], v[178:181], v[126:129]
	v_mfma_f32_16x16x32_bf16 v[122:125], v[142:145], v[178:181], v[122:125]
	v_mfma_f32_16x16x32_bf16 v[118:121], v[134:137], v[186:189], v[118:121]
	v_mfma_f32_16x16x32_bf16 v[114:117], v[142:145], v[186:189], v[114:117]
	v_mfma_f32_16x16x32_bf16 v[102:105], v[134:137], v[208:211], v[102:105]
	v_mfma_f32_16x16x32_bf16 v[98:101], v[142:145], v[208:211], v[98:101]
	v_mfma_f32_16x16x32_bf16 v[86:89], v[134:137], v[216:219], v[86:89]
	v_mfma_f32_16x16x32_bf16 v[82:85], v[142:145], v[216:219], v[82:85]
	v_mfma_f32_16x16x32_bf16 v[110:113], v[146:149], v[172:175], v[110:113]
	v_mfma_f32_16x16x32_bf16 v[106:109], v[164:167], v[172:175], v[106:109]
	v_mfma_f32_16x16x32_bf16 v[94:97], v[146:149], v[182:185], v[94:97]
	v_mfma_f32_16x16x32_bf16 v[90:93], v[164:167], v[182:185], v[90:93]
	v_mfma_f32_16x16x32_bf16 v[78:81], v[146:149], v[190:193], v[78:81]
	v_mfma_f32_16x16x32_bf16 v[74:77], v[164:167], v[190:193], v[74:77]
	v_mfma_f32_16x16x32_bf16 v[70:73], v[146:149], v[212:215], v[70:73]
	v_mfma_f32_16x16x32_bf16 v[66:69], v[164:167], v[212:215], v[66:69]
	v_mfma_f32_16x16x32_bf16 v[110:113], v[160:163], v[178:181], v[110:113]
	v_mfma_f32_16x16x32_bf16 v[106:109], v[168:171], v[178:181], v[106:109]
	v_mfma_f32_16x16x32_bf16 v[94:97], v[160:163], v[186:189], v[94:97]
	v_mfma_f32_16x16x32_bf16 v[90:93], v[168:171], v[186:189], v[90:93]
	v_mfma_f32_16x16x32_bf16 v[78:81], v[160:163], v[208:211], v[78:81]
	v_mfma_f32_16x16x32_bf16 v[74:77], v[168:171], v[208:211], v[74:77]
	v_mfma_f32_16x16x32_bf16 v[70:73], v[160:163], v[216:219], v[70:73]
	v_mfma_f32_16x16x32_bf16 v[66:69], v[168:171], v[216:219], v[66:69]
	s_barrier
	s_add_i32 s40, s40, s59
	v_lshl_add_u64 v[220:221], s[34:35], 0, v[0:1]
	s_mov_b32 m0, s40
	ds_read_b128 v[172:175], v177 offset:16384
	ds_read_b128 v[178:181], v177 offset:17408
	ds_read_b128 v[182:185], v177 offset:18432
	ds_read_b128 v[186:189], v177 offset:19456
	ds_read_b128 v[190:193], v177 offset:20480
	ds_read_b128 v[208:211], v177 offset:21504
	ds_read_b128 v[212:215], v177 offset:22528
	ds_read_b128 v[216:219], v177 offset:23552
	global_load_lds_dwordx4 v[220:221], off
	s_add_i32 m0, s40, 0x2000
	s_add_u32 s40, s34, 0x200000
	v_lshl_add_u64 v[222:223], s[34:35], 0, v[154:155]
	s_addc_u32 s41, s35, 0
	s_add_i32 s27, s27, s59
	global_load_lds_dwordx4 v[222:223], off
	v_lshl_add_u64 v[224:225], s[40:41], 0, v[0:1]
	s_mov_b32 m0, s27
	v_lshl_add_u64 v[226:227], s[36:37], 0, v[152:153]
	global_load_lds_dwordx4 v[224:225], off
	v_lshl_add_u64 v[224:225], s[40:41], 0, v[154:155]
	s_add_i32 m0, s27, 0x2000
	s_nop 0
	global_load_lds_dwordx4 v[224:225], off
	v_lshl_add_u64 v[224:225], s[36:37], 0, v[150:151]
	s_mov_b32 m0, s29
	s_nop 0
	global_load_lds_dwordx4 v[224:225], off
	s_mov_b32 m0, s52
	s_nop 0
	global_load_lds_dwordx4 v[226:227], off
	s_waitcnt vmcnt(8)
	s_waitcnt lgkmcnt(0)
	s_barrier
; #define PG8_STAGE(bufoff, gbase, voff) do { _Pragma("unroll") for (int _i = 0; _i < 2; ++_i) \
;         __builtin_amdgcn_global_load_lds((const unsigned*)((const char*)(gbase) + (voff)[_i]), (PG8_LAS unsigned*)(lds + (bufoff) + ldsw + _i * 8192), 16, 0, 0); } while (0)
; #define PG8_LDA(dst, b, h) do { _Pragma("unroll") for (int m = 0; m < 4; ++m) _Pragma("unroll") for (int k = 0; k < 2; ++k) dst[m][k] = *(const PG8_LAS bf16x8*)(lds + PG8_SA(b, h) + aoff + m * 2048 + k * 1024); } while (0)
; #define PG8_LDB(dst, b, h) do { _Pragma("unroll") for (int n = 0; n < 2; ++n) _Pragma("unroll") for (int k = 0; k < 2; ++k) dst[n][k] = *(const PG8_LAS bf16x8*)(lds + PG8_SB(b, h) + boff + n * 2048 + k * 1024); } while (0)
; #define PG8_MMA(ai, bj, At, Bt) do { __builtin_amdgcn_s_setprio(1); _Pragma("unroll") for (int m = 0; m < 4; ++m) _Pragma("unroll") for (int n = 0; n < 2; ++n) _Pragma("unroll") for (int k = 0; k < 2; ++k) \
;         acc[ai][bj][m][n] = __builtin_amdgcn_mfma_f32_16x16x32_bf16(Bt[n][k], At[m][k], acc[ai][bj][m][n], 0, 0, 0); __builtin_amdgcn_s_setprio(0); } while (0)
; #define PG8_WAIT_V(n) asm volatile("s_waitcnt vmcnt(" #n ")" ::: "memory")
; #define PG8_WAIT_L(n) asm volatile("s_waitcnt lgkmcnt(" #n ")" ::: "memory")
; #define PG8_BAR __builtin_amdgcn_s_barrier()
; #define PG8_SCHED __builtin_amdgcn_sched_barrier(0)
; template <class Epi, class Sched, bool ALIGN_EPI = false, bool SP2 = false>
; __device__ __forceinline__ void gemm_phase(PG8_LAS unsigned char* lds, const Gemm g, const Sched& S, const Epi& E, int wid_in) {
;     ...
;             PG8_WAIT_V(8); PG8_WAIT_L(0); PG8_BAR; PG8_MMA(1, 0, At, B0); PG8_MMA(1, 1, At, B1); PG8_BAR; PG8_SCHED;
;             PG8_LDB(B0, 1, 0); PG8_LDB(B1, 1, 1); PG8_SCHED; PG8_LDA(At, 1, 0); PG8_STAGE(PG8_SA(0, 1), a2 + hstep, voffA);
;             PG8_WAIT_V(8); PG8_WAIT_L(0); PG8_BAR; PG8_MMA(0, 0, At, B0); PG8_MMA(0, 1, At, B1); PG8_BAR; PG8_SCHED;
	s_waitcnt lgkmcnt(0)
	v_mfma_f32_16x16x32_bf16 v[62:65], v[130:133], v[172:175], v[62:65]
	v_mfma_f32_16x16x32_bf16 v[58:61], v[138:141], v[172:175], v[58:61]
	v_mfma_f32_16x16x32_bf16 v[54:57], v[130:133], v[182:185], v[54:57]
	v_mfma_f32_16x16x32_bf16 v[50:53], v[138:141], v[182:185], v[50:53]
	v_mfma_f32_16x16x32_bf16 v[38:41], v[130:133], v[190:193], v[38:41]
	v_mfma_f32_16x16x32_bf16 v[34:37], v[138:141], v[190:193], v[34:37]
	v_mfma_f32_16x16x32_bf16 v[22:25], v[130:133], v[212:215], v[22:25]
	v_mfma_f32_16x16x32_bf16 v[18:21], v[138:141], v[212:215], v[18:21]
	v_mfma_f32_16x16x32_bf16 v[62:65], v[134:137], v[178:181], v[62:65]
	v_mfma_f32_16x16x32_bf16 v[58:61], v[142:145], v[178:181], v[58:61]
	v_mfma_f32_16x16x32_bf16 v[54:57], v[134:137], v[186:189], v[54:57]
	v_mfma_f32_16x16x32_bf16 v[50:53], v[142:145], v[186:189], v[50:53]
	v_mfma_f32_16x16x32_bf16 v[38:41], v[134:137], v[208:211], v[38:41]
	v_mfma_f32_16x16x32_bf16 v[34:37], v[142:145], v[208:211], v[34:37]
	v_mfma_f32_16x16x32_bf16 v[22:25], v[134:137], v[216:219], v[22:25]
	v_mfma_f32_16x16x32_bf16 v[18:21], v[142:145], v[216:219], v[18:21]
	v_mfma_f32_16x16x32_bf16 v[46:49], v[146:149], v[172:175], v[46:49]
	v_mfma_f32_16x16x32_bf16 v[42:45], v[164:167], v[172:175], v[42:45]
	v_mfma_f32_16x16x32_bf16 v[30:33], v[146:149], v[182:185], v[30:33]
	v_mfma_f32_16x16x32_bf16 v[26:29], v[164:167], v[182:185], v[26:29]
	v_mfma_f32_16x16x32_bf16 v[14:17], v[146:149], v[190:193], v[14:17]
	v_mfma_f32_16x16x32_bf16 v[10:13], v[164:167], v[190:193], v[10:13]
	v_mfma_f32_16x16x32_bf16 v[6:9], v[146:149], v[212:215], v[6:9]
	v_mfma_f32_16x16x32_bf16 v[2:5], v[164:167], v[212:215], v[2:5]
	v_mfma_f32_16x16x32_bf16 v[46:49], v[160:163], v[178:181], v[46:49]
	v_mfma_f32_16x16x32_bf16 v[42:45], v[168:171], v[178:181], v[42:45]
	v_mfma_f32_16x16x32_bf16 v[30:33], v[160:163], v[186:189], v[30:33]
	v_mfma_f32_16x16x32_bf16 v[26:29], v[168:171], v[186:189], v[26:29]
	v_mfma_f32_16x16x32_bf16 v[14:17], v[160:163], v[208:211], v[14:17]
	v_mfma_f32_16x16x32_bf16 v[10:13], v[168:171], v[208:211], v[10:13]
	v_mfma_f32_16x16x32_bf16 v[6:9], v[160:163], v[216:219], v[6:9]
	v_mfma_f32_16x16x32_bf16 v[2:5], v[168:171], v[216:219], v[2:5]
	s_barrier
	s_add_i32 s27, 0, 0x18000
	s_add_i32 s40, 0, 0x1c000
	v_add_u32_e32 v142, s27, v176
	v_add_u32_e32 v168, s40, v176
	ds_read_b128 v[130:133], v142
	ds_read_b128 v[134:137], v142 offset:1024
	ds_read_b128 v[138:141], v142 offset:2048
	ds_read_b128 v[142:145], v142 offset:3072
	ds_read_b128 v[146:149], v168
	ds_read_b128 v[160:163], v168 offset:1024
	ds_read_b128 v[164:167], v168 offset:2048
	ds_read_b128 v[168:171], v168 offset:3072
	s_add_u32 s36, s36, 0x200000
	s_addc_u32 s37, s37, 0
	s_mov_b32 m0, s53
	v_lshl_add_u64 v[228:229], s[36:37], 0, v[150:151]
	ds_read_b128 v[172:175], v177 offset:32768
	ds_read_b128 v[178:181], v177 offset:33792
	ds_read_b128 v[182:185], v177 offset:34816
	ds_read_b128 v[186:189], v177 offset:35840
	ds_read_b128 v[190:193], v177 offset:36864
	ds_read_b128 v[208:211], v177 offset:37888
	ds_read_b128 v[212:215], v177 offset:38912
	ds_read_b128 v[216:219], v177 offset:39936
	global_load_lds_dwordx4 v[228:229], off
	v_lshl_add_u64 v[228:229], s[36:37], 0, v[152:153]
	s_mov_b32 m0, s61
	s_nop 0
	global_load_lds_dwordx4 v[228:229], off
	s_waitcnt vmcnt(8)
	s_waitcnt lgkmcnt(0)
	s_barrier
	s_waitcnt lgkmcnt(0)
	v_mfma_f32_16x16x32_bf16 v[126:129], v[130:133], v[172:175], v[126:129]
	v_mfma_f32_16x16x32_bf16 v[122:125], v[138:141], v[172:175], v[122:125]
	v_mfma_f32_16x16x32_bf16 v[118:121], v[130:133], v[182:185], v[118:121]
	v_mfma_f32_16x16x32_bf16 v[114:117], v[138:141], v[182:185], v[114:117]
	v_mfma_f32_16x16x32_bf16 v[102:105], v[130:133], v[190:193], v[102:105]
	v_mfma_f32_16x16x32_bf16 v[98:101], v[138:141], v[190:193], v[98:101]
	v_mfma_f32_16x16x32_bf16 v[86:89], v[130:133], v[212:215], v[86:89]
	v_mfma_f32_16x16x32_bf16 v[82:85], v[138:141], v[212:215], v[82:85]
	v_mfma_f32_16x16x32_bf16 v[126:129], v[134:137], v[178:181], v[126:129]
	v_mfma_f32_16x16x32_bf16 v[122:125], v[142:145], v[178:181], v[122:125]
	v_mfma_f32_16x16x32_bf16 v[118:121], v[134:137], v[186:189], v[118:121]
	v_mfma_f32_16x16x32_bf16 v[114:117], v[142:145], v[186:189], v[114:117]
	v_mfma_f32_16x16x32_bf16 v[102:105], v[134:137], v[208:211], v[102:105]
	v_mfma_f32_16x16x32_bf16 v[98:101], v[142:145], v[208:211], v[98:101]
	v_mfma_f32_16x16x32_bf16 v[86:89], v[134:137], v[216:219], v[86:89]
	v_mfma_f32_16x16x32_bf16 v[82:85], v[142:145], v[216:219], v[82:85]
	v_mfma_f32_16x16x32_bf16 v[110:113], v[146:149], v[172:175], v[110:113]
	v_mfma_f32_16x16x32_bf16 v[106:109], v[164:167], v[172:175], v[106:109]
	v_mfma_f32_16x16x32_bf16 v[94:97], v[146:149], v[182:185], v[94:97]
	v_mfma_f32_16x16x32_bf16 v[90:93], v[164:167], v[182:185], v[90:93]
	v_mfma_f32_16x16x32_bf16 v[78:81], v[146:149], v[190:193], v[78:81]
	v_mfma_f32_16x16x32_bf16 v[74:77], v[164:167], v[190:193], v[74:77]
	v_mfma_f32_16x16x32_bf16 v[70:73], v[146:149], v[212:215], v[70:73]
	v_mfma_f32_16x16x32_bf16 v[66:69], v[164:167], v[212:215], v[66:69]
	v_mfma_f32_16x16x32_bf16 v[110:113], v[160:163], v[178:181], v[110:113]
	v_mfma_f32_16x16x32_bf16 v[106:109], v[168:171], v[178:181], v[106:109]
	v_mfma_f32_16x16x32_bf16 v[94:97], v[160:163], v[186:189], v[94:97]
	v_mfma_f32_16x16x32_bf16 v[90:93], v[168:171], v[186:189], v[90:93]
	v_mfma_f32_16x16x32_bf16 v[78:81], v[160:163], v[208:211], v[78:81]
	v_mfma_f32_16x16x32_bf16 v[74:77], v[168:171], v[208:211], v[74:77]
	v_mfma_f32_16x16x32_bf16 v[70:73], v[160:163], v[216:219], v[70:73]
	v_mfma_f32_16x16x32_bf16 v[66:69], v[168:171], v[216:219], v[66:69]
	s_barrier
; #define PG8_STAGE(bufoff, gbase, voff) do { _Pragma("unroll") for (int _i = 0; _i < 2; ++_i) \
;         __builtin_amdgcn_global_load_lds((const unsigned*)((const char*)(gbase) + (voff)[_i]), (PG8_LAS unsigned*)(lds + (bufoff) + ldsw + _i * 8192), 16, 0, 0); } while (0)
; #define PG8_LDA(dst, b, h) do { _Pragma("unroll") for (int m = 0; m < 4; ++m) _Pragma("unroll") for (int k = 0; k < 2; ++k) dst[m][k] = *(const PG8_LAS bf16x8*)(lds + PG8_SA(b, h) + aoff + m * 2048 + k * 1024); } while (0)
; #define PG8_MMA(ai, bj, At, Bt) do { __builtin_amdgcn_s_setprio(1); _Pragma("unroll") for (int m = 0; m < 4; ++m) _Pragma("unroll") for (int n = 0; n < 2; ++n) _Pragma("unroll") for (int k = 0; k < 2; ++k) \
;         acc[ai][bj][m][n] = __builtin_amdgcn_mfma_f32_16x16x32_bf16(Bt[n][k], At[m][k], acc[ai][bj][m][n], 0, 0, 0); __builtin_amdgcn_s_setprio(0); } while (0)
; #define PG8_WAIT_V(n) asm volatile("s_waitcnt vmcnt(" #n ")" ::: "memory")
; #define PG8_WAIT_L(n) asm volatile("s_waitcnt lgkmcnt(" #n ")" ::: "memory")
; #define PG8_BAR __builtin_amdgcn_s_barrier()
; #define PG8_SCHED __builtin_amdgcn_sched_barrier(0)
; template <class Epi, class Sched, bool ALIGN_EPI = false, bool SP2 = false>
; __device__ __forceinline__ void gemm_phase(PG8_LAS unsigned char* lds, const Gemm g, const Sched& S, const Epi& E, int wid_in) {
;     ...
;         for (int t = 0; t < nt; t += 2) {
;             const bool last = (t == nt - 2);
;             const char* a1 = cA + (size_t)(t + 1) * kstep;
;             const char* a2 = last ? nA : cA + (size_t)(t + 2) * kstep; const char* b2 = last ? nB : cB + (size_t)(t + 2) * kstep;
;     ...
;             PG8_LDA(At, 1, 1); PG8_STAGE(PG8_SB(1, 0), b3, voffB); PG8_STAGE(PG8_SB(1, 1), b3 + hstep, voffB); PG8_STAGE(PG8_SA(1, 0), a3, voffA);
;             PG8_WAIT_V(8); PG8_WAIT_L(0); PG8_BAR; PG8_MMA(1, 0, At, B0); PG8_MMA(1, 1, At, B1); PG8_BAR; PG8_SCHED;
	s_add_i32 s27, s27, s59
	v_lshl_add_u64 v[220:221], v[220:221], 0, s[94:95]
	s_mov_b32 m0, s27
	ds_read_b128 v[172:175], v177 offset:49152
	ds_read_b128 v[178:181], v177 offset:50176
	ds_read_b128 v[182:185], v177 offset:51200
	ds_read_b128 v[186:189], v177 offset:52224
	ds_read_b128 v[190:193], v177 offset:53248
	ds_read_b128 v[208:211], v177 offset:54272
	ds_read_b128 v[212:215], v177 offset:55296
	ds_read_b128 v[216:219], v177 offset:56320
	global_load_lds_dwordx4 v[220:221], off
	s_add_i32 m0, s27, 0x2000
	s_add_u32 s34, s34, 0x200080
	v_lshl_add_u64 v[220:221], v[222:223], 0, s[94:95]
	s_addc_u32 s35, s35, 0
	s_add_i32 s27, s40, s59
	global_load_lds_dwordx4 v[220:221], off
	v_lshl_add_u64 v[220:221], s[34:35], 0, v[0:1]
	s_mov_b32 m0, s27
	s_nop 0
	global_load_lds_dwordx4 v[220:221], off
	v_lshl_add_u64 v[220:221], s[34:35], 0, v[154:155]
	s_add_i32 m0, s27, 0x2000
	s_nop 0
	global_load_lds_dwordx4 v[220:221], off
	v_lshl_add_u64 v[220:221], v[224:225], 0, s[94:95]
	s_mov_b32 m0, s73
	s_nop 0
	global_load_lds_dwordx4 v[220:221], off
	v_lshl_add_u64 v[220:221], v[226:227], 0, s[94:95]
	s_mov_b32 m0, s80
	s_nop 0
	global_load_lds_dwordx4 v[220:221], off
	s_waitcnt vmcnt(8)
	s_waitcnt lgkmcnt(0)
	s_barrier
	s_waitcnt lgkmcnt(0)
	v_mfma_f32_16x16x32_bf16 v[62:65], v[130:133], v[172:175], v[62:65]
	v_mfma_f32_16x16x32_bf16 v[58:61], v[138:141], v[172:175], v[58:61]
	v_mfma_f32_16x16x32_bf16 v[54:57], v[130:133], v[182:185], v[54:57]
	v_mfma_f32_16x16x32_bf16 v[50:53], v[138:141], v[182:185], v[50:53]
	v_mfma_f32_16x16x32_bf16 v[38:41], v[130:133], v[190:193], v[38:41]
	v_mfma_f32_16x16x32_bf16 v[34:37], v[138:141], v[190:193], v[34:37]
	v_mfma_f32_16x16x32_bf16 v[22:25], v[130:133], v[212:215], v[22:25]
	v_mfma_f32_16x16x32_bf16 v[18:21], v[138:141], v[212:215], v[18:21]
	v_mfma_f32_16x16x32_bf16 v[62:65], v[134:137], v[178:181], v[62:65]
	v_mfma_f32_16x16x32_bf16 v[58:61], v[142:145], v[178:181], v[58:61]
	v_mfma_f32_16x16x32_bf16 v[54:57], v[134:137], v[186:189], v[54:57]
	v_mfma_f32_16x16x32_bf16 v[50:53], v[142:145], v[186:189], v[50:53]
	v_mfma_f32_16x16x32_bf16 v[38:41], v[134:137], v[208:211], v[38:41]
	v_mfma_f32_16x16x32_bf16 v[34:37], v[142:145], v[208:211], v[34:37]
	v_mfma_f32_16x16x32_bf16 v[22:25], v[134:137], v[216:219], v[22:25]
	v_mfma_f32_16x16x32_bf16 v[18:21], v[142:145], v[216:219], v[18:21]
	v_mfma_f32_16x16x32_bf16 v[46:49], v[146:149], v[172:175], v[46:49]
	v_mfma_f32_16x16x32_bf16 v[42:45], v[164:167], v[172:175], v[42:45]
	v_mfma_f32_16x16x32_bf16 v[30:33], v[146:149], v[182:185], v[30:33]
	v_mfma_f32_16x16x32_bf16 v[26:29], v[164:167], v[182:185], v[26:29]
	v_mfma_f32_16x16x32_bf16 v[14:17], v[146:149], v[190:193], v[14:17]
	v_mfma_f32_16x16x32_bf16 v[10:13], v[164:167], v[190:193], v[10:13]
	v_mfma_f32_16x16x32_bf16 v[6:9], v[146:149], v[212:215], v[6:9]
	v_mfma_f32_16x16x32_bf16 v[2:5], v[164:167], v[212:215], v[2:5]
	v_mfma_f32_16x16x32_bf16 v[46:49], v[160:163], v[178:181], v[46:49]
	v_mfma_f32_16x16x32_bf16 v[42:45], v[168:171], v[178:181], v[42:45]
	v_mfma_f32_16x16x32_bf16 v[30:33], v[160:163], v[186:189], v[30:33]
	v_mfma_f32_16x16x32_bf16 v[26:29], v[168:171], v[186:189], v[26:29]
	v_mfma_f32_16x16x32_bf16 v[14:17], v[160:163], v[208:211], v[14:17]
	v_mfma_f32_16x16x32_bf16 v[10:13], v[168:171], v[208:211], v[10:13]
	v_mfma_f32_16x16x32_bf16 v[6:9], v[160:163], v[216:219], v[6:9]
	v_mfma_f32_16x16x32_bf16 v[2:5], v[168:171], v[216:219], v[2:5]
	s_barrier
	s_add_u32 s19, s19, 0x100
	s_addc_u32 s21, s21, 0
	s_add_u32 s30, s30, 0x100
	s_addc_u32 s31, s31, 0
	s_cmp_ge_i32 s56, s90
	s_mov_b32 s27, s56
	s_cbranch_scc0 .LBB0_1233
	s_and_b64 vcc, exec, s[14:15]
	s_cbranch_vccz .LBB0_1236
	s_barrier
